# P5 instruction diet: max3 trees, mask index adds only on masked tiles, cmp loops scalar-base DMA + no over-drain, both-active QK with 8 reads in flight
# speedup vs baseline: 1.0361x; 1.0121x over previous
; #define LAS __attribute__((address_space(3)))
; __device__ __forceinline__ void attn_fast(const Ptrs& P, LAS unsigned char* lds, int G, int bid) {
;     const int tid = threadIdx.x, lane = tid & 63, w = __builtin_amdgcn_readfirstlane(tid >> 6), fr = lane & 15, fq = lane >> 4, qi = fr >> 2, hh = fr & 3;
;     LAS float* IMP = (LAS float*)(lds + 98304) + w * (8 * 132);
;     LAS unsigned* SELM = (LAS unsigned*)(lds + 132096);
;     const h16* U = (const h16*)(P.ws + WS_U); h16* Y = (h16*)(P.ws + WS_YACC);
;     const float SC = 0.08838834764831845f * 1.4426950408889634f;
;     const int NEGBIG = -(1 << 30);
;     unsigned kl[4]; kl[0] = (unsigned)lane; kl[1] = kl[2] = kl[3] = 0u;
;     const int vz = (4 * fq + (fr >> 2)) & 7;
;     const unsigned vl0 = (unsigned)((4 * fq + (fr >> 2)) * 256 + 8 * (fr & 1) + 16 * ((fr >> 1) & 1));
;     const int nunits = (512 + G - 1) / G;
.LBB0_501:
.LBB0_502:
	s_cmp_lt_i32 s26, 6
	s_cselect_b64 s[0:1], -1, 0
	s_cmp_gt_i32 s27, 5
	s_cselect_b64 s[4:5], -1, 0
	s_and_b64 s[0:1], s[0:1], s[4:5]
	s_andn2_b64 vcc, exec, s[0:1]
	s_cbranch_vccnz .LBB0_694
	s_abs_i32 s1, s95
	v_cvt_f32_u32_e32 v2, s1
	s_sub_i32 s5, 0, s1
	s_add_i32 s3, s95, 0x1ff
	s_xor_b32 s4, s3, s95
	v_rcp_iflag_f32_e32 v2, v2
	s_abs_i32 s3, s3
	s_ashr_i32 s4, s4, 31
	v_readfirstlane_b32 s0, v1
	v_mul_f32_e32 v2, 0x4f7ffffe, v2
	v_cvt_u32_f32_e32 v2, v2
	v_writelane_b32 v243, s68, 0
	s_mov_b32 s65, 0
	v_readfirstlane_b32 s6, v2
	s_mul_i32 s5, s5, s6
	s_mul_hi_u32 s5, s6, s5
	s_add_i32 s6, s6, s5
	s_mul_hi_u32 s5, s3, s6
	s_mul_i32 s6, s5, s1
	s_sub_i32 s3, s3, s6
	s_add_i32 s7, s5, 1
	s_sub_i32 s6, s3, s1
	s_cmp_ge_u32 s3, s1
	s_cselect_b32 s5, s7, s5
	s_cselect_b32 s3, s6, s3
	s_add_i32 s6, s5, 1
	s_cmp_ge_u32 s3, s1
	s_cselect_b32 s1, s6, s5
	v_writelane_b32 v243, s69, 1
	s_xor_b32 s1, s1, s4
	v_writelane_b32 v243, s78, 2
	s_sub_i32 s12, s1, s4
	s_cmp_lt_i32 s12, 1
	v_writelane_b32 v243, s79, 3
	v_writelane_b32 v243, s76, 4
	s_cbranch_scc1 .LBB0_630
	s_lshr_b32 s0, s0, 6
	s_mul_i32 s1, s0, 0x1080
	s_add_i32 s85, s1, 0
	s_add_i32 s66, s85, 0x18000
	s_add_u32 s18, s24, 0xe564000
	s_addc_u32 s19, s25, 0
	s_add_u32 s20, s24, 0x25564000
	s_addc_u32 s21, s25, 0
	s_cmpk_lg_i32 s95, 0x100
	s_cselect_b64 s[14:15], -1, 0
	s_lshl_b32 s3, s2, 5
	s_and_b32 s3, s3, 32
	s_ashr_i32 s4, s2, 3
	s_add_i32 s3, s3, s4
	s_bfe_u32 s4, s2, 0x20001
	v_writelane_b32 v243, s4, 5
	v_bfe_u32 v4, v1, 4, 2
	v_writelane_b32 v243, s3, 6
	s_sub_i32 s3, 0x7f, s3
	s_lshl_b32 s70, s0, 3
	v_bfe_u32 v5, v1, 2, 2
	v_lshlrev_b32_e32 v173, 2, v4
	v_lshlrev_b32_e32 v2, 3, v1
	s_add_u32 s71, s24, 0x6364000
	v_or_b32_e32 v6, v173, v5
	v_and_b32_e32 v7, 24, v2
	v_and_b32_e32 v8, 3, v1
	s_addc_u32 s72, s25, 0
	v_lshl_or_b32 v174, v6, 8, v7
	v_writelane_b32 v243, s3, 7
	v_lshlrev_b32_e32 v9, 7, v8
	s_add_u32 s73, s24, 0x6464000
	v_cmp_eq_u32_e64 s[10:11], 0, v8
	v_lshlrev_b32_e32 v6, 5, v6
	v_mov_b32_e32 v8, 0xe0
	s_movk_i32 s3, 0x60
	s_addc_u32 s74, s25, 0
	s_lshl_b32 s75, s0, 11
	s_movk_i32 s0, 0xe0
	v_bitop3_b32 v180, v6, s3, v8 bitop3:0x6c
	s_movk_i32 s77, 0x80
	s_movk_i32 s3, 0xa0
	s_movk_i32 s78, 0xc0
	v_and_b32_e32 v177, 0xe0, v6
	v_bitop3_b32 v178, v6, 32, v8 bitop3:0x6c
	v_bitop3_b32 v179, v6, 64, v8 bitop3:0x6c
	v_bitop3_b32 v181, v6, s77, v8 bitop3:0x6c
	v_bitop3_b32 v182, v6, s3, v8 bitop3:0x6c
	v_bitop3_b32 v183, v6, s78, v8 bitop3:0x6c
	v_bitop3_b32 v184, v6, s0, v6 bitop3:0xc
	s_movk_i32 s3, 0x210
	v_mov_b32_e32 v6, s1
	v_mad_u32_u24 v6, v5, s3, v6
	v_or_b32_e32 v189, v6, v173
	v_add_u32_e32 v6, 0, v184
	v_lshlrev_b32_e32 v8, 10, v4
	s_movk_i32 s1, 0x4000
	v_add3_u32 v190, v6, v8, s1
	v_add_u32_e32 v6, 0, v183
	v_add3_u32 v192, v6, v8, s1
	v_add_u32_e32 v6, 0, v182
	v_add3_u32 v193, v6, v8, s1
	v_add_u32_e32 v6, 0, v181
	v_add3_u32 v194, v6, v8, s1
	v_add_u32_e32 v6, 0, v180
	v_add3_u32 v195, v6, v8, s1
	v_add_u32_e32 v6, 0, v179
	v_writelane_b32 v243, s96, 8
	v_or_b32_e32 v175, s70, v5
	v_lshlrev_b32_e32 v2, 3, v4
	v_lshlrev_b32_e32 v176, 6, v4
	v_lshl_or_b32 v191, v5, 8, v7
	v_add3_u32 v196, v6, v8, s1
	v_add_u32_e32 v6, 0, v178
	v_lshlrev_b32_e32 v4, 7, v4
	v_lshlrev_b32_e32 v5, 5, v5
	v_writelane_b32 v243, s97, 9
	v_and_b32_e32 v172, 63, v1
	s_add_i32 s76, s75, 0
	v_add3_u32 v197, v6, v8, s1
	v_add_u32_e32 v6, 0, v8
	v_bitop3_b32 v4, v4, s0, v5 bitop3:0xc8
	v_mbcnt_lo_u32_b32 v203, -1, 0
	v_writelane_b32 v243, s12, 10
	v_mov_b32_e32 v3, 0
	v_cmp_eq_u32_e64 s[4:5], 0, v172
	v_or_b32_e32 v185, 64, v172
	s_or_b32 s79, s75, 0x400
	v_lshlrev_b32_e32 v186, 4, v175
	v_or_b32_e32 v187, 0xffffffc0, v172
	v_lshl_add_u32 v188, v172, 2, s66
	s_add_i32 s80, s70, 0x80
	s_add_i32 s81, s75, 0x14400
	s_add_i32 s82, s75, 0x10400
	s_add_i32 s83, s75, 0x14000
	s_add_i32 s84, s75, 0x10000
	v_add3_u32 v198, v6, v4, s1
	s_add_i32 s85, s85, 0x18210
	s_movk_i32 s86, 0x2e00
	v_lshlrev_b32_e32 v166, 1, v2
	v_lshlrev_b32_e32 v199, 1, v9
	s_mov_b64 s[30:31], 0x4000
	s_add_i32 s87, s76, 0x8000
	s_mov_b64 s[34:35], 0x4400
	s_add_i32 s88, s76, 0x8400
	s_mov_b32 s89, 0x3e0293ee
	s_add_i32 s90, s76, 0x4400
	s_add_i32 s91, s76, 0xc000
	s_add_i32 s92, s76, 0xc400
	s_movk_i32 s93, 0x2000
	v_mov_b32_e32 v200, 0x3b8637bd
	v_mov_b32_e32 v201, 0x461c4000
	v_mov_b32_e32 v202, 0xff61b1e6
	v_mbcnt_hi_u32_b32 v204, -1, v203
	v_mov_b32_e32 v205, 0x2e00
	v_mov_b32_e32 v206, 0xf149f2ca
	v_writelane_b32 v243, s14, 11
	s_nop 1
	v_writelane_b32 v243, s15, 12
	v_lshrrev_b32_e32 v4, 4, v172
	v_add_u32_e32 v4, s70, v4
	v_and_b32_e32 v5, 15, v172
	v_mul_u32_u24_e32 v6, 0x2e00, v4
	v_xor_b32_e32 v7, v4, v5
	v_and_b32_e32 v7, 15, v7
	v_lshl_add_u32 v244, v7, 4, v6
	v_lshlrev_b32_e32 v7, 1, v4
	v_and_b32_e32 v7, 14, v7
	v_xor_b32_e32 v7, v7, v5
	v_lshl_add_u32 v245, v7, 4, v6
	v_add_u32_e32 v245, 0x200, v245
	v_add_u32_e32 v4, 4, v4
	v_add_u32_e32 v6, 0xb800, v6
	v_xor_b32_e32 v7, v4, v5
	v_and_b32_e32 v7, 15, v7
	v_lshl_add_u32 v246, v7, 4, v6
	v_lshlrev_b32_e32 v7, 1, v4
	v_and_b32_e32 v7, 14, v7
	v_xor_b32_e32 v7, v7, v5
	v_lshl_add_u32 v247, v7, 4, v6
	v_add_u32_e32 v247, 0x200, v247
	v_lshrrev_b32_e32 v4, 4, v172
	v_add_u32_e32 v4, s70, v4
	v_lshlrev_b32_e32 v6, 8, v4
	v_xor_b32_e32 v7, v4, v5
	v_and_b32_e32 v7, 15, v7
	v_lshl_add_u32 v250, v7, 4, v6
	v_lshlrev_b32_e32 v7, 1, v4
	v_and_b32_e32 v7, 14, v7
	v_xor_b32_e32 v7, v7, v5
	v_lshl_add_u32 v251, v7, 4, v6
	v_add_u32_e32 v4, 4, v4
	v_add_u32_e32 v6, 0x400, v6
	v_xor_b32_e32 v7, v4, v5
	v_and_b32_e32 v7, 15, v7
	v_lshl_add_u32 v252, v7, 4, v6
	v_lshlrev_b32_e32 v7, 1, v4
	v_and_b32_e32 v7, 14, v7
	v_xor_b32_e32 v7, v7, v5
	v_lshl_add_u32 v253, v7, 4, v6
	s_branch .LBB0_506

; #define AF_WAITV(n) asm volatile("s_waitcnt vmcnt(" #n ")" ::: "memory")
; #define AF_BAR() do { __builtin_amdgcn_s_barrier(); asm volatile("" ::: "memory"); } while (0)
; __device__ __forceinline__ void attn_fast(const Ptrs& P, LAS unsigned char* lds, int G, int bid) {
;     ...
;                 if (T + 1 < ntc) AF_WAITV(2); else AF_WAITV(0);
;                 AF_BAR();
;                 if (T + 2 < ntc) AF_ISSUE((T + 2) % 3, KC, VC, 128, 64 * (T + 2), false);
;                 af_qk<true, true>(lds + (T % 3) * 32768, kl, qf, s);
; #pragma unroll
;                 for (int ct = 0; ct < 2; ++ct) {
;                     if (1024 * T + 1039 > 64 * qb) af_maskraw(s[ct], 1024 * T + 31, 16, fq, tq[ct], NEGBIG);
.LBB0_525:
	s_barrier
	s_add_i32 s23, s22, 2
	s_cmp_gt_i32 s23, s14
	s_cbranch_scc1 .LBB0_527
	s_mul_hi_u32 s23, s1, 0xaaaaaaab
	s_lshr_b32 s23, s23, 1
	s_mul_i32 s23, s23, 0x18000
	s_sub_i32 s23, s17, s23
	s_sub_i32 s98, s16, s70
	s_lshl_b32 s98, s98, 8
	s_add_u32 s98, s8, s98
	s_addc_u32 s99, s9, 0
	s_add_i32 m0, s23, 0x10000
	s_nop 0
	global_load_lds_dwordx4 v250, s[98:99]
	s_add_i32 m0, s23, 0x10400
	s_nop 0
	global_load_lds_dwordx4 v252, s[98:99]
.LBB0_527:
	s_mul_hi_u32 s23, s22, 0xaaaaaaab
	s_lshr_b32 s23, s23, 1
	s_mul_i32 s23, s23, 0x18000
	v_mov_b32 v2, v172
	s_sub_i32 s23, s3, s23
	v_and_b32_e32 v38, 15, v2
	v_lshlrev_b32_e32 v58, 8, v38
	v_lshlrev_b32_e32 v38, 4, v38
	v_bitop3_b32 v2, v38, v2, -16 bitop3:0x78
	s_add_i32 s23, s23, 0
	v_add3_u32 v76, v2, v58, s23
	ds_read_b128 v[38:41], v76
	ds_read_b128 v[46:49], v76 offset:4096
	v_xor_b32_e32 v50, 64, v2
	v_add3_u32 v77, v50, v58, s23
	s_waitcnt lgkmcnt(0)
	v_mfma_f32_16x16x32_f16 v[42:45], v[38:41], v[6:9], 0
	ds_read_b128 v[50:53], v77
	ds_read_b128 v[54:57], v77 offset:4096
	v_xor_b32_e32 v59, 0x80, v2
	v_add3_u32 v80, v59, v58, s23
	v_mfma_f32_16x16x32_f16 v[38:41], v[38:41], v[22:25], 0
	v_xor_b32_e32 v2, 0xc0, v2
	v_add3_u32 v2, v2, v58, s23
	s_waitcnt lgkmcnt(1)
	v_mfma_f32_16x16x32_f16 v[42:45], v[50:53], v[10:13], v[42:45]
	v_mfma_f32_16x16x32_f16 v[38:41], v[50:53], v[26:29], v[38:41]
	ds_read_b128 v[50:53], v80
	ds_read_b128 v[62:65], v80 offset:4096
	s_waitcnt lgkmcnt(1)
	v_mfma_f32_16x16x32_f16 v[42:45], v[50:53], v[14:17], v[42:45]
	v_mfma_f32_16x16x32_f16 v[38:41], v[50:53], v[30:33], v[38:41]
	ds_read_b128 v[50:53], v2
	ds_read_b128 v[66:69], v2 offset:4096
	s_waitcnt lgkmcnt(1)
	v_mfma_f32_16x16x32_f16 v[58:61], v[50:53], v[18:21], v[42:45]
	v_mfma_f32_16x16x32_f16 v[42:45], v[50:53], v[34:37], v[38:41]
	v_mfma_f32_16x16x32_f16 v[38:41], v[46:49], v[6:9], 0
	v_mfma_f32_16x16x32_f16 v[46:49], v[46:49], v[22:25], 0
	v_mfma_f32_16x16x32_f16 v[38:41], v[54:57], v[10:13], v[38:41]
	v_mfma_f32_16x16x32_f16 v[46:49], v[54:57], v[26:29], v[46:49]
	v_mfma_f32_16x16x32_f16 v[38:41], v[62:65], v[14:17], v[38:41]
	v_mfma_f32_16x16x32_f16 v[46:49], v[62:65], v[30:33], v[46:49]
	s_waitcnt lgkmcnt(0)
	v_mfma_f32_16x16x32_f16 v[62:65], v[66:69], v[18:21], v[38:41]
	s_nop 4
	ds_read_b128 v[38:41], v76 offset:8192
	ds_read_b128 v[50:53], v77 offset:8192
	ds_read_b128 v[54:57], v80 offset:8192
	ds_read_b128 v[72:75], v2 offset:8192
	v_mfma_f32_16x16x32_f16 v[46:49], v[66:69], v[34:37], v[46:49]
	s_waitcnt lgkmcnt(3)
	v_mfma_f32_16x16x32_f16 v[66:69], v[38:41], v[6:9], 0
	v_mfma_f32_16x16x32_f16 v[38:41], v[38:41], v[22:25], 0
	s_waitcnt lgkmcnt(2)
	v_mfma_f32_16x16x32_f16 v[66:69], v[50:53], v[10:13], v[66:69]
	v_mfma_f32_16x16x32_f16 v[38:41], v[50:53], v[26:29], v[38:41]
	s_waitcnt lgkmcnt(1)
	v_mfma_f32_16x16x32_f16 v[50:53], v[54:57], v[14:17], v[66:69]
	v_mfma_f32_16x16x32_f16 v[38:41], v[54:57], v[30:33], v[38:41]
	ds_read_b128 v[54:57], v76 offset:12288
	ds_read_b128 v[76:79], v77 offset:12288
	ds_read_b128 v[80:83], v80 offset:12288
	ds_read_b128 v[84:87], v2 offset:12288
	s_waitcnt lgkmcnt(4)
	v_mfma_f32_16x16x32_f16 v[66:69], v[72:75], v[18:21], v[50:53]
	v_mfma_f32_16x16x32_f16 v[50:53], v[72:75], v[34:37], v[38:41]
	s_waitcnt lgkmcnt(3)
	v_mfma_f32_16x16x32_f16 v[38:41], v[54:57], v[6:9], 0
	v_mfma_f32_16x16x32_f16 v[54:57], v[54:57], v[22:25], 0
	s_waitcnt lgkmcnt(2)
	v_mfma_f32_16x16x32_f16 v[38:41], v[76:79], v[10:13], v[38:41]
	v_mfma_f32_16x16x32_f16 v[54:57], v[76:79], v[26:29], v[54:57]
	s_waitcnt lgkmcnt(1)
	v_mfma_f32_16x16x32_f16 v[38:41], v[80:83], v[14:17], v[38:41]
	v_mfma_f32_16x16x32_f16 v[72:75], v[80:83], v[30:33], v[54:57]
	s_waitcnt lgkmcnt(0)
	v_mfma_f32_16x16x32_f16 v[54:57], v[84:87], v[18:21], v[38:41]
	v_mfma_f32_16x16x32_f16 v[38:41], v[84:87], v[34:37], v[72:75]
	s_cmp_gt_i32 s0, s33
	v_add_u32_e32 v2, s0, v176
	s_cselect_b64 s[52:53], -1, 0
	s_cmp_le_i32 s0, s33
	v_add_u32_e32 v90, 0xfffffc10, v2
	v_add_u32_e32 v89, 0xfffffc20, v2
	v_add_u32_e32 v88, 0xfffffc30, v2
	v_add_u32_e32 v87, 0xfffffc40, v2
	v_add_u32_e32 v86, 0xfffffd10, v2
	v_add_u32_e32 v85, 0xfffffd20, v2
	v_add_u32_e32 v84, 0xfffffd30, v2
	v_add_u32_e32 v83, 0xfffffd40, v2
	v_add_u32_e32 v82, 0xfffffe10, v2
	v_add_u32_e32 v81, 0xfffffe20, v2
	v_add_u32_e32 v79, 0xfffffe30, v2
	v_add_u32_e32 v78, 0xfffffe40, v2
	v_add_u32_e32 v77, 0xffffff10, v2
	v_add_u32_e32 v76, 0xffffff20, v2
	v_add_u32_e32 v75, 0xffffff30, v2
	v_add_u32_e32 v74, 0xffffff40, v2
	s_cbranch_scc1 .LBB0_529
	v_cmp_le_i32_e32 vcc, v90, v208
	s_nop 1
	v_cndmask_b32_e32 v58, v202, v58, vcc
	v_cmp_le_i32_e32 vcc, v89, v208
	s_nop 1
	v_cndmask_b32_e32 v59, v202, v59, vcc
	v_cmp_le_i32_e32 vcc, v88, v208
	s_nop 1
	v_cndmask_b32_e32 v60, v202, v60, vcc
	v_cmp_le_i32_e32 vcc, v87, v208
	s_nop 1
	v_cndmask_b32_e32 v61, v202, v61, vcc
	v_cmp_le_i32_e32 vcc, v86, v208
	s_nop 1
	v_cndmask_b32_e32 v62, v202, v62, vcc
	v_cmp_le_i32_e32 vcc, v85, v208
	s_nop 1
	v_cndmask_b32_e32 v63, v202, v63, vcc
	v_cmp_le_i32_e32 vcc, v84, v208
	s_nop 1
	v_cndmask_b32_e32 v64, v202, v64, vcc
	v_cmp_le_i32_e32 vcc, v83, v208
	s_nop 1
	v_cndmask_b32_e32 v65, v202, v65, vcc
	v_cmp_le_i32_e32 vcc, v82, v208
	s_nop 1
	v_cndmask_b32_e32 v66, v202, v66, vcc
	v_cmp_le_i32_e32 vcc, v81, v208
	s_nop 1
	v_cndmask_b32_e32 v67, v202, v67, vcc
	v_cmp_le_i32_e32 vcc, v79, v208
	s_nop 1
	v_cndmask_b32_e32 v68, v202, v68, vcc
	v_cmp_le_i32_e32 vcc, v78, v208
	s_nop 1
	v_cndmask_b32_e32 v69, v202, v69, vcc
	v_cmp_le_i32_e32 vcc, v77, v208
	s_nop 1
	v_cndmask_b32_e32 v54, v202, v54, vcc
	v_cmp_le_i32_e32 vcc, v76, v208
	s_nop 1
	v_cndmask_b32_e32 v55, v202, v55, vcc
	v_cmp_le_i32_e32 vcc, v75, v208
	s_nop 1
	v_cndmask_b32_e32 v56, v202, v56, vcc
	v_cmp_le_i32_e32 vcc, v74, v208
	s_nop 1
	v_cndmask_b32_e32 v57, v202, v57, vcc

; __device__ __forceinline__ float af_rawmax(const f32x4 (&s)[4]) {
;     float v = fmaxf(fmaxf(s[0][0], s[0][1]), fmaxf(s[0][2], s[0][3]));
; #pragma unroll
;     for (int kt = 1; kt < 4; ++kt) v = fmaxf(v, fmaxf(fmaxf(s[kt][0], s[kt][1]), fmaxf(s[kt][2], s[kt][3])));
;     v = fmaxf(v, __shfl_xor(v, 16)); v = fmaxf(v, __shfl_xor(v, 32)); return v;
; }
; __device__ __forceinline__ void attn_fast(const Ptrs& P, LAS unsigned char* lds, int G, int bid) {
;     ...
;                     const float mn = fmaxf(m[ct], af_rawmax(s[ct]) * SC); const float al = __builtin_amdgcn_exp2f(m[ct] - mn); m[ct] = mn; float ps = 0.f;
; #pragma unroll
;                     for (int kt = 0; kt < 4; ++kt)
; #pragma unroll
;                         for (int jj = 0; jj < 4; ++jj) ps += __builtin_amdgcn_exp2f(__builtin_fmaf(s[ct][kt][jj], SC, -mn));
;                     l[ct] = l[ct] * al + ps; }
.LBB0_531:
	s_waitcnt lgkmcnt(0)
	v_max_f32_e32 v74, v92, v92
	v_max_f32_e32 v75, v91, v91
	v_max_f32_e32 v74, v75, v74
	v_mul_f32_e32 v74, 0x3e0293ee, v74
	v_max_f32_e32 v75, v5, v5
	v_max_f32_e32 v136, v75, v74
	v_fma_f32 v58, v58, s89, -v136
	v_exp_f32_e32 v58, v58
	v_fma_f32 v59, v59, s89, -v136
	v_exp_f32_e32 v59, v59
	v_fma_f32 v60, v60, s89, -v136
	v_exp_f32_e32 v60, v60
	v_fma_f32 v61, v61, s89, -v136
	v_exp_f32_e32 v61, v61
	v_add_f32_e32 v58, 0, v58
	v_fma_f32 v62, v62, s89, -v136
	v_exp_f32_e32 v62, v62
	v_add_f32_e32 v58, v59, v58
	v_fma_f32 v59, v63, s89, -v136
	v_add_f32_e32 v58, v60, v58
	v_exp_f32_e32 v59, v59
	v_fma_f32 v60, v64, s89, -v136
	v_add_f32_e32 v58, v61, v58
	v_exp_f32_e32 v60, v60
	v_fma_f32 v61, v65, s89, -v136
	v_exp_f32_e32 v61, v61
	v_add_f32_e32 v58, v62, v58
	v_fma_f32 v62, v66, s89, -v136
	v_exp_f32_e32 v62, v62
	v_add_f32_e32 v58, v59, v58
	v_fma_f32 v59, v67, s89, -v136
	v_add_f32_e32 v58, v60, v58
	v_exp_f32_e32 v59, v59
	v_fma_f32 v60, v68, s89, -v136
	v_add_f32_e32 v58, v61, v58
	v_exp_f32_e32 v60, v60
	v_fma_f32 v61, v69, s89, -v136
	v_exp_f32_e32 v61, v61
	v_fma_f32 v54, v54, s89, -v136
	v_add_f32_e32 v58, v62, v58
	v_exp_f32_e32 v54, v54
	v_add_f32_e32 v58, v59, v58
	v_add_f32_e32 v58, v60, v58
	v_add_f32_e32 v58, v61, v58
	v_add_f32_e32 v54, v54, v58
	v_max3_f32 v58, v43, v42, v45
	v_max3_f32 v59, v44, v49, v48
	v_max3_f32 v60, v46, v47, v53
	v_max3_f32 v61, v52, v41, v40
	v_max3_f32 v58, v58, v50, v51
	v_max3_f32 v59, v59, v38, v39
	v_max3_f32 v58, v58, v59, v60
	v_max_f32_e32 v58, v58, v61
	ds_bpermute_b32 v2, v2, v58
	v_fma_f32 v55, v55, s89, -v136
	v_exp_f32_e32 v55, v55
	v_sub_f32_e32 v5, v5, v136
	v_exp_f32_e32 v59, v5
	s_waitcnt lgkmcnt(0)
	v_max_f32_e32 v2, v2, v2
	v_max_f32_e32 v2, v58, v2
	ds_bpermute_b32 v58, v80, v2
	v_add_f32_e32 v5, v55, v54
	v_fma_f32 v56, v56, s89, -v136
	v_exp_f32_e32 v56, v56
	v_fma_f32 v57, v57, s89, -v136
	s_waitcnt lgkmcnt(0)
	v_max_f32_e32 v54, v58, v58
	v_max_f32_e32 v2, v2, v54
	v_mul_f32_e32 v2, 0x3e0293ee, v2
	v_max_f32_e32 v54, v4, v4
	v_max_f32_e32 v137, v54, v2
	v_sub_f32_e32 v2, v4, v137
	v_fma_f32 v4, v42, s89, -v137
	v_exp_f32_e32 v4, v4
	v_fma_f32 v42, v43, s89, -v137
	v_exp_f32_e32 v42, v42
	v_fma_f32 v43, v44, s89, -v137
	v_exp_f32_e32 v43, v43
	v_fma_f32 v44, v45, s89, -v137
	v_exp_f32_e32 v44, v44
	v_add_f32_e32 v4, 0, v4
	v_add_f32_e32 v4, v42, v4
	v_fma_f32 v42, v46, s89, -v137
	v_add_f32_e32 v4, v43, v4
	v_exp_f32_e32 v42, v42
	v_fma_f32 v43, v47, s89, -v137
	v_add_f32_e32 v4, v44, v4
	v_exp_f32_e32 v43, v43
	v_fma_f32 v44, v48, s89, -v137
	v_exp_f32_e32 v44, v44
	v_fma_f32 v45, v49, s89, -v137
	v_exp_f32_e32 v45, v45
	v_add_f32_e32 v4, v42, v4
	v_fma_f32 v42, v50, s89, -v137
	v_add_f32_e32 v4, v43, v4
	v_exp_f32_e32 v42, v42
	v_fma_f32 v43, v51, s89, -v137
	v_add_f32_e32 v4, v44, v4
	v_exp_f32_e32 v43, v43
	v_fma_f32 v44, v52, s89, -v137
	v_add_f32_e32 v4, v45, v4
	v_exp_f32_e32 v44, v44
	v_fma_f32 v45, v53, s89, -v137
	v_exp_f32_e32 v45, v45
	v_fma_f32 v38, v38, s89, -v137
	v_add_f32_e32 v4, v42, v4
	v_exp_f32_e32 v38, v38
	v_fma_f32 v39, v39, s89, -v137
	v_add_f32_e32 v4, v43, v4
	v_exp_f32_e32 v39, v39
	v_fma_f32 v40, v40, s89, -v137
	v_add_f32_e32 v4, v44, v4
	v_exp_f32_e32 v40, v40
	v_fma_f32 v41, v41, s89, -v137
	v_exp_f32_e32 v57, v57
	v_add_f32_e32 v4, v45, v4
	v_exp_f32_e32 v41, v41
	v_add_f32_e32 v4, v38, v4
	v_exp_f32_e32 v2, v2
	v_add_f32_e32 v4, v39, v4
	v_add_f32_e32 v5, v56, v5
	v_add_f32_e32 v4, v40, v4
	v_add_f32_e32 v5, v57, v5
	v_add_f32_e32 v4, v41, v4
	s_addk_i32 s0, 0x400
	s_add_i32 s17, s17, 0x8000
	s_add_i32 s1, s1, 1
	s_add_i32 s3, s3, 0x8000
	s_add_i32 s16, s16, 64
	s_add_i32 s23, s22, 1
	v_fmac_f32_e32 v5, v71, v59
	s_cmp_eq_u32 s22, s14
	v_fmac_f32_e32 v4, v70, v2
	s_cbranch_scc0 .LBB0_521
	s_mov_b64 s[52:53], 0

; #define AF_WAITV(n) asm volatile("s_waitcnt vmcnt(" #n ")" ::: "memory")
; #define AF_BAR() do { __builtin_amdgcn_s_barrier(); asm volatile("" ::: "memory"); } while (0)
; __device__ __forceinline__ void attn_fast(const Ptrs& P, LAS unsigned char* lds, int G, int bid) {
;     ...
;                 if (T + 1 < ntc) AF_WAITV(4); else AF_WAITV(0);
;                 AF_BAR();
;                 if (T + 2 < ntc) AF_ISSUE((T + 2) % 3, KC, VC, 128, 64 * (T + 2), true);
;                 af_qk<true, true>(lds + (T % 3) * 32768, kl, qf, s);
;                 half8 pf[2][2];
; #pragma unroll
;                 for (int ct = 0; ct < 2; ++ct) {
;                     if (1024 * T + 1039 > 64 * qb) af_maskraw(s[ct], 1024 * T + 31, 16, fq, tq[ct], NEGBIG);
.LBB0_543:
	s_barrier
	s_add_i32 s6, s22, 2
	s_cmp_gt_i32 s6, s14
	s_cbranch_scc1 .LBB0_545
	s_mul_hi_u32 s6, s1, 0xaaaaaaab
	s_lshr_b32 s6, s6, 1
	s_mul_i32 s6, s6, 0x18000
	s_sub_i32 s6, s3, s6
	s_sub_i32 s98, s17, s70
	s_lshl_b32 s98, s98, 8
	s_add_u32 s100, s12, s98
	s_addc_u32 s101, s13, 0
	s_add_u32 s98, s8, s98
	s_addc_u32 s99, s9, 0
	s_add_i32 m0, s6, s84
	s_nop 0
	global_load_lds_dwordx4 v250, s[98:99]
	s_add_i32 m0, s6, s83
	s_nop 0
	global_load_lds_dwordx4 v251, s[100:101]
	s_add_i32 m0, s6, s82
	s_nop 0
	global_load_lds_dwordx4 v252, s[98:99]
	s_add_i32 m0, s6, s81
	s_nop 0
	global_load_lds_dwordx4 v253, s[100:101]
.LBB0_545:
	s_mul_hi_u32 s6, s22, 0xaaaaaaab
	s_lshr_b32 s23, s6, 1
	s_mul_i32 s23, s23, 0x18000
	v_mov_b32 v2, v172
	s_add_i32 s6, s3, 0
	v_and_b32_e32 v102, 15, v2
	v_lshlrev_b32_e32 v118, 8, v102
	v_lshlrev_b32_e32 v102, 4, v102
	s_sub_i32 s6, s6, s23
	v_bitop3_b32 v2, v102, v2, -16 bitop3:0x78
	s_addk_i32 s6, 0x2000
	v_add3_u32 v141, v2, v118, s6
	v_add_u32_e32 v102, 0xffffe000, v141
	ds_read_b128 v[102:105], v102
	v_xor_b32_e32 v106, 64, v2
	v_add3_u32 v150, v106, v118, s6
	v_add_u32_e32 v106, 0xffffe000, v150
	ds_read_b128 v[106:109], v106
	v_xor_b32_e32 v114, 0x80, v2
	v_add3_u32 v151, v114, v118, s6
	s_waitcnt lgkmcnt(0)
	v_mfma_f32_16x16x32_f16 v[110:113], v[102:105], v[6:9], 0
	v_add_u32_e32 v114, 0xffffe000, v151
	ds_read_b128 v[114:117], v114
	v_xor_b32_e32 v2, 0xc0, v2
	v_mfma_f32_16x16x32_f16 v[102:105], v[102:105], v[22:25], 0
	v_add3_u32 v2, v2, v118, s6
	v_add_u32_e32 v118, 0xfffff000, v141
	v_add_u32_e32 v122, 0xfffff000, v150
	v_mfma_f32_16x16x32_f16 v[110:113], v[106:109], v[10:13], v[110:113]
	v_mfma_f32_16x16x32_f16 v[102:105], v[106:109], v[26:29], v[102:105]
	v_add_u32_e32 v106, 0xffffe000, v2
	ds_read_b128 v[106:109], v106
	ds_read_b128 v[118:121], v118
	ds_read_b128 v[122:125], v122
	s_waitcnt lgkmcnt(3)
	v_mfma_f32_16x16x32_f16 v[110:113], v[114:117], v[14:17], v[110:113]
	v_mfma_f32_16x16x32_f16 v[102:105], v[114:117], v[30:33], v[102:105]
	v_add_u32_e32 v114, 0xfffff000, v151
	v_add_u32_e32 v115, 0xfffff000, v2
	s_waitcnt lgkmcnt(2)
	v_mfma_f32_16x16x32_f16 v[130:133], v[106:109], v[18:21], v[110:113]
	s_nop 2
	ds_read_b128 v[110:113], v114
	ds_read_b128 v[142:145], v115
	v_mfma_f32_16x16x32_f16 v[114:117], v[106:109], v[34:37], v[102:105]
	s_waitcnt lgkmcnt(3)
	v_mfma_f32_16x16x32_f16 v[102:105], v[118:121], v[6:9], 0
	v_mfma_f32_16x16x32_f16 v[106:109], v[118:121], v[22:25], 0
	s_waitcnt lgkmcnt(2)
	v_mfma_f32_16x16x32_f16 v[102:105], v[122:125], v[10:13], v[102:105]
	v_mfma_f32_16x16x32_f16 v[106:109], v[122:125], v[26:29], v[106:109]
	s_waitcnt lgkmcnt(1)
	v_mfma_f32_16x16x32_f16 v[102:105], v[110:113], v[14:17], v[102:105]
	v_mfma_f32_16x16x32_f16 v[106:109], v[110:113], v[30:33], v[106:109]
	s_waitcnt lgkmcnt(0)
	v_mfma_f32_16x16x32_f16 v[126:129], v[142:145], v[18:21], v[102:105]
	s_nop 4
	ds_read_b128 v[102:105], v141
	ds_read_b128 v[118:121], v150
	ds_read_b128 v[122:125], v151
	ds_read_b128 v[146:149], v2
	v_mfma_f32_16x16x32_f16 v[110:113], v[142:145], v[34:37], v[106:109]
	s_waitcnt lgkmcnt(3)
	v_mfma_f32_16x16x32_f16 v[106:109], v[102:105], v[6:9], 0
	v_mfma_f32_16x16x32_f16 v[102:105], v[102:105], v[22:25], 0
	s_waitcnt lgkmcnt(2)
	v_mfma_f32_16x16x32_f16 v[106:109], v[118:121], v[10:13], v[106:109]
	v_mfma_f32_16x16x32_f16 v[102:105], v[118:121], v[26:29], v[102:105]
	ds_read_b128 v[118:121], v141 offset:4096
	ds_read_b128 v[142:145], v150 offset:4096
	ds_read_b128 v[150:153], v151 offset:4096
	ds_read_b128 v[154:157], v2 offset:4096
	s_waitcnt lgkmcnt(5)
	v_mfma_f32_16x16x32_f16 v[106:109], v[122:125], v[14:17], v[106:109]
	v_mfma_f32_16x16x32_f16 v[102:105], v[122:125], v[30:33], v[102:105]
	s_waitcnt lgkmcnt(4)
	v_mfma_f32_16x16x32_f16 v[122:125], v[146:149], v[18:21], v[106:109]
	v_mfma_f32_16x16x32_f16 v[106:109], v[146:149], v[34:37], v[102:105]
	s_waitcnt lgkmcnt(3)
	v_mfma_f32_16x16x32_f16 v[102:105], v[118:121], v[6:9], 0
	v_mfma_f32_16x16x32_f16 v[118:121], v[118:121], v[22:25], 0
	s_waitcnt lgkmcnt(2)
	v_mfma_f32_16x16x32_f16 v[102:105], v[142:145], v[10:13], v[102:105]
	v_mfma_f32_16x16x32_f16 v[118:121], v[142:145], v[26:29], v[118:121]
	s_waitcnt lgkmcnt(1)
	v_mfma_f32_16x16x32_f16 v[102:105], v[150:153], v[14:17], v[102:105]
	v_mfma_f32_16x16x32_f16 v[142:145], v[150:153], v[30:33], v[118:121]
	s_waitcnt lgkmcnt(0)
	v_mfma_f32_16x16x32_f16 v[118:121], v[154:157], v[18:21], v[102:105]
	v_mfma_f32_16x16x32_f16 v[102:105], v[154:157], v[34:37], v[142:145]
	s_cmp_gt_i32 s16, s33
	v_add_u32_e32 v2, s16, v176
	s_cselect_b64 s[6:7], -1, 0
	s_cmp_le_i32 s16, s33
	v_add_u32_e32 v160, 0xfffffc10, v2
	v_add_u32_e32 v159, 0xfffffc20, v2
	v_add_u32_e32 v158, 0xfffffc30, v2
	v_add_u32_e32 v157, 0xfffffc40, v2
	v_add_u32_e32 v156, 0xfffffd10, v2
	v_add_u32_e32 v155, 0xfffffd20, v2
	v_add_u32_e32 v154, 0xfffffd30, v2
	v_add_u32_e32 v153, 0xfffffd40, v2
	v_add_u32_e32 v152, 0xfffffe10, v2
	v_add_u32_e32 v151, 0xfffffe20, v2
	v_add_u32_e32 v150, 0xfffffe30, v2
	v_add_u32_e32 v149, 0xfffffe40, v2
	v_add_u32_e32 v148, 0xffffff10, v2
	v_add_u32_e32 v147, 0xffffff20, v2
	v_add_u32_e32 v146, 0xffffff30, v2
	v_add_u32_e32 v145, 0xffffff40, v2
	s_cbranch_scc1 .LBB0_547
	v_cmp_le_i32_e32 vcc, v160, v208
	s_nop 1
	v_cndmask_b32_e32 v130, v202, v130, vcc
	v_cmp_le_i32_e32 vcc, v159, v208
	s_nop 1
	v_cndmask_b32_e32 v131, v202, v131, vcc
	v_cmp_le_i32_e32 vcc, v158, v208
	s_nop 1
	v_cndmask_b32_e32 v132, v202, v132, vcc
	v_cmp_le_i32_e32 vcc, v157, v208
	s_nop 1
	v_cndmask_b32_e32 v133, v202, v133, vcc
	v_cmp_le_i32_e32 vcc, v156, v208
	s_nop 1
	v_cndmask_b32_e32 v126, v202, v126, vcc
	v_cmp_le_i32_e32 vcc, v155, v208
	s_nop 1
	v_cndmask_b32_e32 v127, v202, v127, vcc
	v_cmp_le_i32_e32 vcc, v154, v208
	s_nop 1
	v_cndmask_b32_e32 v128, v202, v128, vcc
	v_cmp_le_i32_e32 vcc, v153, v208
	s_nop 1
	v_cndmask_b32_e32 v129, v202, v129, vcc
	v_cmp_le_i32_e32 vcc, v152, v208
	s_nop 1
	v_cndmask_b32_e32 v122, v202, v122, vcc
	v_cmp_le_i32_e32 vcc, v151, v208
	s_nop 1
	v_cndmask_b32_e32 v123, v202, v123, vcc
	v_cmp_le_i32_e32 vcc, v150, v208
	s_nop 1
	v_cndmask_b32_e32 v124, v202, v124, vcc
	v_cmp_le_i32_e32 vcc, v149, v208
	s_nop 1
	v_cndmask_b32_e32 v125, v202, v125, vcc
	v_cmp_le_i32_e32 vcc, v148, v208
	s_nop 1
	v_cndmask_b32_e32 v118, v202, v118, vcc
	v_cmp_le_i32_e32 vcc, v147, v208
	s_nop 1
	v_cndmask_b32_e32 v119, v202, v119, vcc
	v_cmp_le_i32_e32 vcc, v146, v208
	s_nop 1
	v_cndmask_b32_e32 v120, v202, v120, vcc
	v_cmp_le_i32_e32 vcc, v145, v208
	s_nop 1
	v_cndmask_b32_e32 v121, v202, v121, vcc

; __device__ __forceinline__ void af_online_fast(f32x4 (&s)[4], bool colsel, float& m, float& l, f32x4 (&o)[8], half8 (&pf)[2], float SC) {
;     float lm = fmaxf(fmaxf(s[0][0], s[0][1]), fmaxf(s[0][2], s[0][3]));
; #pragma unroll
;     for (int kt = 1; kt < 4; ++kt) lm = fmaxf(lm, fmaxf(fmaxf(s[kt][0], s[kt][1]), fmaxf(s[kt][2], s[kt][3])));
;     if (__ballot(colsel && (lm * SC > m + 8.f)) != 0ull) {
;         float v = lm; v = fmaxf(v, __shfl_xor(v, 16)); v = fmaxf(v, __shfl_xor(v, 32));
;         const float mloc = colsel ? v * SC : -1.0e30f;
;         const float mn = fmaxf(m, mloc); const float al = __builtin_amdgcn_exp2f(m - mn); m = mn;
;         l *= al;
; #pragma unroll
;         for (int dt = 0; dt < 8; ++dt) o[dt] *= al;
;     }
.LBB0_599:
	v_max3_f32 v151, v115, v114, v117
	v_max3_f32 v118, v116, v113, v112
	v_max3_f32 v119, v110, v111, v109
	v_max3_f32 v120, v108, v106, v107
	s_nop 1
	v_max3_f32 v151, v151, v105, v104
	v_max3_f32 v118, v118, v102, v103
	v_max3_f32 v151, v151, v118, v119
	v_max_f32_e32 v151, v151, v120
	v_mul_f32_e32 v118, 0x3e0293ee, v151
	v_add_f32_e32 v119, 0x41000000, v4
	v_cmp_lt_i32_e64 s[6:7], -1, v2
	v_cmp_gt_f32_e32 vcc, v118, v119
	v_mov_b64_e32 v[148:149], v[96:97]
	v_mov_b64_e32 v[144:145], v[88:89]
	v_mov_b64_e32 v[136:137], v[84:85]
	v_mov_b64_e32 v[140:141], v[76:77]
	v_mov_b64_e32 v[120:121], v[68:69]
	v_mov_b64_e32 v[124:125], v[64:65]
	v_mov_b64_e32 v[128:129], v[52:53]
	v_mov_b64_e32 v[132:133], v[48:49]
	s_and_b64 vcc, s[6:7], vcc
	v_mov_b64_e32 v[146:147], v[94:95]
	v_mov_b64_e32 v[142:143], v[86:87]
	v_mov_b64_e32 v[134:135], v[82:83]
	v_mov_b64_e32 v[138:139], v[74:75]
	v_mov_b64_e32 v[118:119], v[66:67]
	v_mov_b64_e32 v[122:123], v[62:63]
	v_mov_b64_e32 v[126:127], v[50:51]
	v_mov_b64_e32 v[130:131], v[46:47]
	v_mov_b32_e32 v150, v5
	v_mov_b32_e32 v224, v4
	s_cbranch_vccz .LBB0_601
	ds_bpermute_b32 v118, v167, v151
	v_max_f32_e32 v119, v151, v151
	v_max_f32_e32 v120, v4, v4
	s_waitcnt lgkmcnt(0)
	v_max_f32_e32 v118, v118, v118
	v_max_f32_e32 v118, v119, v118
	ds_bpermute_b32 v119, v207, v118
	s_waitcnt lgkmcnt(0)
	v_max_f32_e32 v119, v119, v119
	v_max_f32_e32 v118, v118, v119
	v_mul_f32_e32 v118, 0x3e0293ee, v118
	v_cndmask_b32_e64 v118, v206, v118, s[6:7]
	v_max_f32_e32 v224, v120, v118
	v_sub_f32_e32 v118, v4, v224
	v_exp_f32_e32 v130, v118
	s_nop 0
	v_mul_f32_e32 v150, v5, v130
	v_pk_mul_f32 v[148:149], v[96:97], v[130:131] op_sel_hi:[1,0]
	v_pk_mul_f32 v[146:147], v[94:95], v[130:131] op_sel_hi:[1,0]
	v_pk_mul_f32 v[144:145], v[88:89], v[130:131] op_sel_hi:[1,0]
	v_pk_mul_f32 v[142:143], v[86:87], v[130:131] op_sel_hi:[1,0]
	v_pk_mul_f32 v[136:137], v[84:85], v[130:131] op_sel_hi:[1,0]
	v_pk_mul_f32 v[134:135], v[82:83], v[130:131] op_sel_hi:[1,0]
	v_pk_mul_f32 v[140:141], v[76:77], v[130:131] op_sel_hi:[1,0]
	v_pk_mul_f32 v[138:139], v[74:75], v[130:131] op_sel_hi:[1,0]
	v_pk_mul_f32 v[120:121], v[68:69], v[130:131] op_sel_hi:[1,0]
	v_pk_mul_f32 v[118:119], v[66:67], v[130:131] op_sel_hi:[1,0]
	v_pk_mul_f32 v[124:125], v[64:65], v[130:131] op_sel_hi:[1,0]
	v_pk_mul_f32 v[122:123], v[62:63], v[130:131] op_sel_hi:[1,0]
	v_pk_mul_f32 v[128:129], v[52:53], v[130:131] op_sel_hi:[1,0]
	v_pk_mul_f32 v[126:127], v[50:51], v[130:131] op_sel_hi:[1,0]
	v_pk_mul_f32 v[132:133], v[48:49], v[130:131] op_sel_hi:[1,0]
	v_pk_mul_f32 v[130:131], v[46:47], v[130:131] op_sel_hi:[1,0]

; __device__ __forceinline__ void af_online_fast(f32x4 (&s)[4], bool colsel, float& m, float& l, f32x4 (&o)[8], half8 (&pf)[2], float SC) {
;     float lm = fmaxf(fmaxf(s[0][0], s[0][1]), fmaxf(s[0][2], s[0][3]));
; #pragma unroll
;     for (int kt = 1; kt < 4; ++kt) lm = fmaxf(lm, fmaxf(fmaxf(s[kt][0], s[kt][1]), fmaxf(s[kt][2], s[kt][3])));
;     if (__ballot(colsel && (lm * SC > m + 8.f)) != 0ull) {
;         float v = lm; v = fmaxf(v, __shfl_xor(v, 16)); v = fmaxf(v, __shfl_xor(v, 32));
;         const float mloc = colsel ? v * SC : -1.0e30f;
;         const float mn = fmaxf(m, mloc); const float al = __builtin_amdgcn_exp2f(m - mn); m = mn;
;         l *= al;
; #pragma unroll
;         for (int dt = 0; dt < 8; ++dt) o[dt] *= al;
;     }
.LBB0_606:
	v_max3_f32 v151, v123, v122, v125
	v_max3_f32 v114, v124, v113, v112
	v_max3_f32 v115, v110, v111, v109
	v_max3_f32 v116, v108, v106, v107
	s_nop 1
	v_max3_f32 v151, v151, v105, v104
	v_max3_f32 v114, v114, v102, v103
	v_max3_f32 v151, v151, v114, v115
	v_max_f32_e32 v151, v151, v116
	v_mul_f32_e32 v114, 0x3e0293ee, v151
	v_add_f32_e32 v115, 0x41000000, v217
	v_cmp_lt_i32_e64 s[6:7], -1, v219
	v_cmp_gt_f32_e32 vcc, v114, v115
	v_mov_b64_e32 v[116:117], v[40:41]
	v_mov_b64_e32 v[120:121], v[44:45]
	v_mov_b64_e32 v[128:129], v[56:57]
	v_mov_b64_e32 v[132:133], v[60:61]
	v_mov_b64_e32 v[148:149], v[72:73]
	v_mov_b64_e32 v[144:145], v[80:81]
	v_mov_b64_e32 v[140:141], v[92:93]
	v_mov_b64_e32 v[136:137], v[100:101]
	s_and_b64 vcc, s[6:7], vcc
	v_mov_b64_e32 v[114:115], v[38:39]
	v_mov_b64_e32 v[118:119], v[42:43]
	v_mov_b64_e32 v[126:127], v[54:55]
	v_mov_b64_e32 v[130:131], v[58:59]
	v_mov_b64_e32 v[146:147], v[70:71]
	v_mov_b64_e32 v[142:143], v[78:79]
	v_mov_b64_e32 v[138:139], v[90:91]
	v_mov_b64_e32 v[134:135], v[98:99]
	v_mov_b32_e32 v150, v216
	v_mov_b32_e32 v221, v217
	s_cbranch_vccz .LBB0_608
	ds_bpermute_b32 v114, v167, v151
	v_max_f32_e32 v115, v151, v151
	v_max_f32_e32 v116, v217, v217
	s_waitcnt lgkmcnt(0)
	v_max_f32_e32 v114, v114, v114
	v_max_f32_e32 v114, v115, v114
	ds_bpermute_b32 v115, v207, v114
	s_waitcnt lgkmcnt(0)
	v_max_f32_e32 v115, v115, v115
	v_max_f32_e32 v114, v114, v115
	v_mul_f32_e32 v114, 0x3e0293ee, v114
	v_cndmask_b32_e64 v114, v206, v114, s[6:7]
	v_max_f32_e32 v221, v116, v114
	v_sub_f32_e32 v114, v217, v221
	v_exp_f32_e32 v114, v114
	s_nop 0
	v_mul_f32_e32 v150, v216, v114
	v_pk_mul_f32 v[136:137], v[100:101], v[114:115] op_sel_hi:[1,0]
	v_pk_mul_f32 v[134:135], v[98:99], v[114:115] op_sel_hi:[1,0]
	v_pk_mul_f32 v[140:141], v[92:93], v[114:115] op_sel_hi:[1,0]
	v_pk_mul_f32 v[138:139], v[90:91], v[114:115] op_sel_hi:[1,0]
	v_pk_mul_f32 v[144:145], v[80:81], v[114:115] op_sel_hi:[1,0]
	v_pk_mul_f32 v[142:143], v[78:79], v[114:115] op_sel_hi:[1,0]
	v_pk_mul_f32 v[148:149], v[72:73], v[114:115] op_sel_hi:[1,0]
	v_pk_mul_f32 v[146:147], v[70:71], v[114:115] op_sel_hi:[1,0]
	v_pk_mul_f32 v[132:133], v[60:61], v[114:115] op_sel_hi:[1,0]
	v_pk_mul_f32 v[130:131], v[58:59], v[114:115] op_sel_hi:[1,0]
	v_pk_mul_f32 v[128:129], v[56:57], v[114:115] op_sel_hi:[1,0]
	v_pk_mul_f32 v[126:127], v[54:55], v[114:115] op_sel_hi:[1,0]
	v_pk_mul_f32 v[120:121], v[44:45], v[114:115] op_sel_hi:[1,0]
	v_pk_mul_f32 v[118:119], v[42:43], v[114:115] op_sel_hi:[1,0]
	v_pk_mul_f32 v[116:117], v[40:41], v[114:115] op_sel_hi:[1,0]
	v_pk_mul_f32 v[114:115], v[38:39], v[114:115] op_sel_hi:[1,0]

; #define LAS __attribute__((address_space(3)))
; template <bool a0, bool a1> __device__ __forceinline__ void af_qk(const LAS unsigned char* kbuf, const unsigned (&kl)[4], const half8 (&qf)[2][4], f32x4 (&s)[2][4]) {
;     const LAS unsigned char* ka[4];
;     { int _ln; asm volatile("v_mov_b32 %0, %1" : "=v"(_ln) : "v"(kl[0]));
;       const int fr_ = _ln & 15, e_ = (_ln >> 4) ^ fr_;
; #pragma unroll
;       for (int ks = 0; ks < 4; ++ks) ka[ks] = kbuf + fr_ * 256 + ((e_ ^ (4 * ks)) << 4); }
;     half8 kf[2][4];
; #pragma unroll
;     for (int ks = 0; ks < 4; ++ks) kf[0][ks] = *(const LAS half8*)(ka[ks]);
; #pragma unroll
;     for (int kt = 0; kt < 4; ++kt) {
;         if (kt < 3) {
; #pragma unroll
;             for (int ks = 0; ks < 4; ++ks) kf[(kt + 1) & 1][ks] = *(const LAS half8*)(ka[ks] + (kt + 1) * 4096); }
;         s[0][kt] = (f32x4){0.f, 0.f, 0.f, 0.f}; s[1][kt] = (f32x4){0.f, 0.f, 0.f, 0.f};
; #pragma unroll
;         for (int ks = 0; ks < 4; ++ks) {
;             if (a0) s[0][kt] = __builtin_amdgcn_mfma_f32_16x16x32_f16(kf[kt & 1][ks], qf[0][ks], s[0][kt], 0, 0, 0);
;             if (a1) s[1][kt] = __builtin_amdgcn_mfma_f32_16x16x32_f16(kf[kt & 1][ks], qf[1][ks], s[1][kt], 0, 0, 0); }
;         __builtin_amdgcn_sched_barrier(0);
;     }
; __device__ __forceinline__ void af_maskraw(f32x4 (&s)[4], int mbase, int mstep, int fq, int hi, int lo) {
; #pragma unroll
;     for (int kt = 0; kt < 4; ++kt)
; #pragma unroll
;         for (int jj = 0; jj < 4; ++jj) { const int met = mbase + mstep * (16 * kt + 4 * fq + jj); s[kt][jj] = (met <= hi && met > lo) ? s[kt][jj] : -3.0e38f; }
; }
.LBB0_610:
	s_andn2_b64 vcc, exec, s[6:7]
	s_cbranch_vccnz .LBB0_619
	v_mov_b32 v102, v172
	s_nop 0
	v_and_b32_e32 v103, 15, v102
	v_lshl_add_u32 v126, v103, 8, s64
	v_lshlrev_b32_e32 v103, 4, v103
	v_bitop3_b32 v127, v103, v102, -16 bitop3:0x78
	v_add_u32_e32 v102, v126, v127
	v_xad_u32 v103, v127, 64, v126
	v_xad_u32 v104, v127, s77, v126
	v_xad_u32 v105, v127, s78, v126
	ds_read_b128 v[134:137], v102
	ds_read_b128 v[138:141], v103
	ds_read_b128 v[142:145], v104
	ds_read_b128 v[146:149], v105
	ds_read_b128 v[150:153], v102 offset:4096
	ds_read_b128 v[154:157], v103 offset:4096
	ds_read_b128 v[158:161], v104 offset:4096
	ds_read_b128 v[162:165], v105 offset:4096
	s_waitcnt lgkmcnt(4)
	v_mfma_f32_16x16x32_f16 v[130:133], v[134:137], v[6:9], 0
	v_mfma_f32_16x16x32_f16 v[114:117], v[134:137], v[22:25], 0
	v_mfma_f32_16x16x32_f16 v[130:133], v[138:141], v[10:13], v[130:133]
	v_mfma_f32_16x16x32_f16 v[114:117], v[138:141], v[26:29], v[114:117]
	v_mfma_f32_16x16x32_f16 v[130:133], v[142:145], v[14:17], v[130:133]
	v_mfma_f32_16x16x32_f16 v[114:117], v[142:145], v[30:33], v[114:117]
	v_mfma_f32_16x16x32_f16 v[130:133], v[146:149], v[18:21], v[130:133]
	v_mfma_f32_16x16x32_f16 v[114:117], v[146:149], v[34:37], v[114:117]
	ds_read_b128 v[134:137], v102 offset:8192
	ds_read_b128 v[138:141], v103 offset:8192
	ds_read_b128 v[142:145], v104 offset:8192
	ds_read_b128 v[146:149], v105 offset:8192
	s_waitcnt lgkmcnt(4)
	v_mfma_f32_16x16x32_f16 v[126:129], v[150:153], v[6:9], 0
	v_mfma_f32_16x16x32_f16 v[110:113], v[150:153], v[22:25], 0
	v_mfma_f32_16x16x32_f16 v[126:129], v[154:157], v[10:13], v[126:129]
	v_mfma_f32_16x16x32_f16 v[110:113], v[154:157], v[26:29], v[110:113]
	v_mfma_f32_16x16x32_f16 v[126:129], v[158:161], v[14:17], v[126:129]
	v_mfma_f32_16x16x32_f16 v[110:113], v[158:161], v[30:33], v[110:113]
	v_mfma_f32_16x16x32_f16 v[126:129], v[162:165], v[18:21], v[126:129]
	v_mfma_f32_16x16x32_f16 v[110:113], v[162:165], v[34:37], v[110:113]
	ds_read_b128 v[150:153], v102 offset:12288
	ds_read_b128 v[154:157], v103 offset:12288
	ds_read_b128 v[158:161], v104 offset:12288
	ds_read_b128 v[162:165], v105 offset:12288
	s_waitcnt lgkmcnt(4)
	v_mfma_f32_16x16x32_f16 v[122:125], v[134:137], v[6:9], 0
	v_mfma_f32_16x16x32_f16 v[106:109], v[134:137], v[22:25], 0
	v_mfma_f32_16x16x32_f16 v[122:125], v[138:141], v[10:13], v[122:125]
	v_mfma_f32_16x16x32_f16 v[106:109], v[138:141], v[26:29], v[106:109]
	v_mfma_f32_16x16x32_f16 v[122:125], v[142:145], v[14:17], v[122:125]
	v_mfma_f32_16x16x32_f16 v[106:109], v[142:145], v[30:33], v[106:109]
	v_mfma_f32_16x16x32_f16 v[122:125], v[146:149], v[18:21], v[122:125]
	v_mfma_f32_16x16x32_f16 v[106:109], v[146:149], v[34:37], v[106:109]
	s_waitcnt lgkmcnt(0)
	v_mfma_f32_16x16x32_f16 v[118:121], v[150:153], v[6:9], 0
	v_mfma_f32_16x16x32_f16 v[102:105], v[150:153], v[22:25], 0
	v_mfma_f32_16x16x32_f16 v[118:121], v[154:157], v[10:13], v[118:121]
	v_mfma_f32_16x16x32_f16 v[102:105], v[154:157], v[26:29], v[102:105]
	v_mfma_f32_16x16x32_f16 v[118:121], v[158:161], v[14:17], v[118:121]
	v_mfma_f32_16x16x32_f16 v[102:105], v[158:161], v[30:33], v[102:105]
	v_mfma_f32_16x16x32_f16 v[118:121], v[162:165], v[18:21], v[118:121]
	v_mfma_f32_16x16x32_f16 v[102:105], v[162:165], v[34:37], v[102:105]
	s_nop 5
	v_cndmask_b32_e64 v134, 0, 1, s[60:61]
	v_cmp_ne_u32_e64 s[8:9], 1, v134
	s_andn2_b64 vcc, exec, s[60:61]
	s_cbranch_vccnz .LBB0_613
	v_add_u32_e32 v148, s16, v173
	v_add_u32_e32 v147, 2, v148
	v_add_u32_e32 v146, 3, v148
	v_add_u32_e32 v145, 16, v148
	v_add_u32_e32 v144, 17, v148
	v_add_u32_e32 v143, 18, v148
	v_add_u32_e32 v142, 19, v148
	v_add_u32_e32 v141, 32, v148
	v_add_u32_e32 v140, 33, v148
	v_add_u32_e32 v139, 34, v148
	v_add_u32_e32 v138, 35, v148
	v_add_u32_e32 v137, 48, v148
	v_add_u32_e32 v136, 49, v148
	v_add_u32_e32 v135, 50, v148
	v_add_u32_e32 v134, 51, v148
	v_cmp_le_i32_e32 vcc, v148, v219
	v_cmp_gt_i32_e64 s[6:7], v148, v220
	s_and_b64 vcc, vcc, s[6:7]
	v_cndmask_b32_e32 v130, v202, v130, vcc
	v_cmp_lt_i32_e32 vcc, v148, v219
	v_cmp_ge_i32_e64 s[6:7], v148, v220
	s_and_b64 vcc, vcc, s[6:7]
	v_cndmask_b32_e32 v131, v202, v131, vcc
	v_cmp_le_i32_e32 vcc, v147, v219
	v_cmp_gt_i32_e64 s[6:7], v147, v220
	s_and_b64 vcc, vcc, s[6:7]
	v_cndmask_b32_e32 v132, v202, v132, vcc
	v_cmp_le_i32_e32 vcc, v146, v219
	v_cmp_gt_i32_e64 s[6:7], v146, v220
	s_and_b64 vcc, vcc, s[6:7]
	v_cndmask_b32_e32 v133, v202, v133, vcc
	v_cmp_le_i32_e32 vcc, v145, v219
	v_cmp_gt_i32_e64 s[6:7], v145, v220
	s_and_b64 vcc, vcc, s[6:7]
	v_cndmask_b32_e32 v126, v202, v126, vcc
	v_cmp_le_i32_e32 vcc, v144, v219
	v_cmp_gt_i32_e64 s[6:7], v144, v220
	s_and_b64 vcc, vcc, s[6:7]
	v_cndmask_b32_e32 v127, v202, v127, vcc
	v_cmp_le_i32_e32 vcc, v143, v219
	v_cmp_gt_i32_e64 s[6:7], v143, v220
	s_and_b64 vcc, vcc, s[6:7]
	v_cndmask_b32_e32 v128, v202, v128, vcc
	v_cmp_le_i32_e32 vcc, v142, v219
	v_cmp_gt_i32_e64 s[6:7], v142, v220
	s_and_b64 vcc, vcc, s[6:7]
	v_cndmask_b32_e32 v129, v202, v129, vcc
	v_cmp_le_i32_e32 vcc, v141, v219
	v_cmp_gt_i32_e64 s[6:7], v141, v220
	s_and_b64 vcc, vcc, s[6:7]
	v_cndmask_b32_e32 v122, v202, v122, vcc
	v_cmp_le_i32_e32 vcc, v140, v219
	v_cmp_gt_i32_e64 s[6:7], v140, v220
	s_and_b64 vcc, vcc, s[6:7]
	v_cndmask_b32_e32 v123, v202, v123, vcc
	v_cmp_le_i32_e32 vcc, v139, v219
	v_cmp_gt_i32_e64 s[6:7], v139, v220
	s_and_b64 vcc, vcc, s[6:7]
	v_cndmask_b32_e32 v124, v202, v124, vcc
	v_cmp_le_i32_e32 vcc, v138, v219
	v_cmp_gt_i32_e64 s[6:7], v138, v220
	s_and_b64 vcc, vcc, s[6:7]
	v_cndmask_b32_e32 v125, v202, v125, vcc
	v_cmp_le_i32_e32 vcc, v137, v219
	v_cmp_gt_i32_e64 s[6:7], v137, v220
	s_and_b64 vcc, vcc, s[6:7]
	v_cndmask_b32_e32 v118, v202, v118, vcc
	v_cmp_le_i32_e32 vcc, v136, v219
	v_cmp_gt_i32_e64 s[6:7], v136, v220
	s_and_b64 vcc, vcc, s[6:7]
	v_cndmask_b32_e32 v119, v202, v119, vcc
	v_cmp_le_i32_e32 vcc, v135, v219
	v_cmp_gt_i32_e64 s[6:7], v135, v220
	s_and_b64 vcc, vcc, s[6:7]
	v_cndmask_b32_e32 v120, v202, v120, vcc
	v_cmp_le_i32_e32 vcc, v134, v219
	v_cmp_gt_i32_e64 s[6:7], v134, v220
	s_and_b64 vcc, vcc, s[6:7]
	v_cndmask_b32_e32 v121, v202, v121, vcc
; __device__ __forceinline__ void af_online_fast(f32x4 (&s)[4], bool colsel, float& m, float& l, f32x4 (&o)[8], half8 (&pf)[2], float SC) {
;     float lm = fmaxf(fmaxf(s[0][0], s[0][1]), fmaxf(s[0][2], s[0][3]));
; #pragma unroll
;     for (int kt = 1; kt < 4; ++kt) lm = fmaxf(lm, fmaxf(fmaxf(s[kt][0], s[kt][1]), fmaxf(s[kt][2], s[kt][3])));
;     if (__ballot(colsel && (lm * SC > m + 8.f)) != 0ull) {
;         float v = lm; v = fmaxf(v, __shfl_xor(v, 16)); v = fmaxf(v, __shfl_xor(v, 32));
;         const float mloc = colsel ? v * SC : -1.0e30f;
;         const float mn = fmaxf(m, mloc); const float al = __builtin_amdgcn_exp2f(m - mn); m = mn;
;         l *= al;
; #pragma unroll
;         for (int dt = 0; dt < 8; ++dt) o[dt] *= al;
;     }
.LBB0_613:
	v_max3_f32 v149, v131, v130, v133
	v_max3_f32 v150, v132, v129, v128
	v_max3_f32 v151, v126, v127, v125
	v_max3_f32 v152, v124, v121, v120
	v_max3_f32 v149, v149, v122, v123
	v_max3_f32 v150, v150, v118, v119
	v_max3_f32 v149, v149, v150, v151
	v_max_f32_e32 v149, v149, v152
	v_mul_f32_e32 v150, 0x3e0293ee, v149
	v_add_f32_e32 v151, 0x41000000, v217
	v_cmp_lt_i32_e64 s[6:7], -1, v219
	v_cmp_gt_f32_e32 vcc, v150, v151
	s_and_b64 vcc, s[6:7], vcc
	s_cbranch_vccz .LBB0_621
	ds_bpermute_b32 v150, v167, v149
	v_max_f32_e32 v149, v149, v149
	s_waitcnt lgkmcnt(0)
	v_max_f32_e32 v150, v150, v150
	v_max_f32_e32 v149, v149, v150
	ds_bpermute_b32 v150, v207, v149
	s_waitcnt lgkmcnt(0)
	v_max_f32_e32 v150, v150, v150
	v_max_f32_e32 v149, v149, v150
	v_mul_f32_e32 v149, 0x3e0293ee, v149
	v_cndmask_b32_e64 v149, v206, v149, s[6:7]
	v_max_f32_e32 v150, v217, v217
	v_max_f32_e32 v221, v150, v149
	v_sub_f32_e32 v149, v217, v221
	v_exp_f32_e32 v150, v149
	s_nop 0
	v_mul_f32_e32 v216, v216, v150
	v_pk_mul_f32 v[100:101], v[100:101], v[150:151] op_sel_hi:[1,0]
	v_pk_mul_f32 v[98:99], v[98:99], v[150:151] op_sel_hi:[1,0]
	v_pk_mul_f32 v[92:93], v[92:93], v[150:151] op_sel_hi:[1,0]
	v_pk_mul_f32 v[90:91], v[90:91], v[150:151] op_sel_hi:[1,0]
	v_pk_mul_f32 v[80:81], v[80:81], v[150:151] op_sel_hi:[1,0]
	v_pk_mul_f32 v[78:79], v[78:79], v[150:151] op_sel_hi:[1,0]
	v_pk_mul_f32 v[72:73], v[72:73], v[150:151] op_sel_hi:[1,0]
	v_pk_mul_f32 v[70:71], v[70:71], v[150:151] op_sel_hi:[1,0]
	v_pk_mul_f32 v[60:61], v[60:61], v[150:151] op_sel_hi:[1,0]
	v_pk_mul_f32 v[58:59], v[58:59], v[150:151] op_sel_hi:[1,0]
	v_pk_mul_f32 v[56:57], v[56:57], v[150:151] op_sel_hi:[1,0]
	v_pk_mul_f32 v[54:55], v[54:55], v[150:151] op_sel_hi:[1,0]
	v_pk_mul_f32 v[44:45], v[44:45], v[150:151] op_sel_hi:[1,0]
	v_pk_mul_f32 v[42:43], v[42:43], v[150:151] op_sel_hi:[1,0]
	v_pk_mul_f32 v[40:41], v[40:41], v[150:151] op_sel_hi:[1,0]
	v_pk_mul_f32 v[38:39], v[38:39], v[150:151] op_sel_hi:[1,0]
	s_and_b64 vcc, exec, s[8:9]
	s_cbranch_vccnz .LBB0_616

; __device__ __forceinline__ void af_online_fast(f32x4 (&s)[4], bool colsel, float& m, float& l, f32x4 (&o)[8], half8 (&pf)[2], float SC) {
;     float lm = fmaxf(fmaxf(s[0][0], s[0][1]), fmaxf(s[0][2], s[0][3]));
; #pragma unroll
;     for (int kt = 1; kt < 4; ++kt) lm = fmaxf(lm, fmaxf(fmaxf(s[kt][0], s[kt][1]), fmaxf(s[kt][2], s[kt][3])));
;     if (__ballot(colsel && (lm * SC > m + 8.f)) != 0ull) {
;         float v = lm; v = fmaxf(v, __shfl_xor(v, 16)); v = fmaxf(v, __shfl_xor(v, 32));
;         const float mloc = colsel ? v * SC : -1.0e30f;
;         const float mn = fmaxf(m, mloc); const float al = __builtin_amdgcn_exp2f(m - mn); m = mn;
;         l *= al;
; #pragma unroll
;         for (int dt = 0; dt < 8; ++dt) o[dt] *= al;
;     }
.LBB0_616:
	v_cmp_lt_i32_e64 s[8:9], -1, v2
	v_max3_f32 v2, v115, v114, v117
	v_max3_f32 v134, v116, v113, v112
	v_max3_f32 v135, v110, v111, v109
	v_max3_f32 v136, v108, v105, v104
	v_max3_f32 v2, v2, v106, v107
	v_max3_f32 v134, v134, v102, v103
	v_max3_f32 v2, v2, v134, v135
	v_max_f32_e32 v2, v2, v136
	v_mul_f32_e32 v134, 0x3e0293ee, v2
	v_add_f32_e32 v135, 0x41000000, v4
	v_cmp_gt_f32_e32 vcc, v134, v135
	s_and_b64 vcc, s[8:9], vcc
	s_cbranch_vccz .LBB0_618
	ds_bpermute_b32 v134, v167, v2
	v_max_f32_e32 v2, v2, v2
	s_waitcnt lgkmcnt(0)
	v_max_f32_e32 v134, v134, v134
	v_max_f32_e32 v2, v2, v134
	ds_bpermute_b32 v134, v207, v2
	s_waitcnt lgkmcnt(0)
	v_max_f32_e32 v134, v134, v134
	v_max_f32_e32 v2, v2, v134
	v_mul_f32_e32 v2, 0x3e0293ee, v2
	v_cndmask_b32_e64 v2, v206, v2, s[8:9]
	v_max_f32_e32 v134, v4, v4
	v_max_f32_e32 v134, v134, v2
	v_sub_f32_e32 v2, v4, v134
	v_exp_f32_e32 v2, v2
	v_mov_b32_e32 v4, v134
	v_mul_f32_e32 v5, v5, v2
	v_pk_mul_f32 v[96:97], v[96:97], v[2:3] op_sel_hi:[1,0]
	v_pk_mul_f32 v[94:95], v[94:95], v[2:3] op_sel_hi:[1,0]
	v_pk_mul_f32 v[88:89], v[88:89], v[2:3] op_sel_hi:[1,0]
	v_pk_mul_f32 v[86:87], v[86:87], v[2:3] op_sel_hi:[1,0]
	v_pk_mul_f32 v[84:85], v[84:85], v[2:3] op_sel_hi:[1,0]
	v_pk_mul_f32 v[82:83], v[82:83], v[2:3] op_sel_hi:[1,0]
	v_pk_mul_f32 v[76:77], v[76:77], v[2:3] op_sel_hi:[1,0]
	v_pk_mul_f32 v[74:75], v[74:75], v[2:3] op_sel_hi:[1,0]
	v_pk_mul_f32 v[68:69], v[68:69], v[2:3] op_sel_hi:[1,0]
	v_pk_mul_f32 v[66:67], v[66:67], v[2:3] op_sel_hi:[1,0]
	v_pk_mul_f32 v[64:65], v[64:65], v[2:3] op_sel_hi:[1,0]
	v_pk_mul_f32 v[62:63], v[62:63], v[2:3] op_sel_hi:[1,0]
	v_pk_mul_f32 v[52:53], v[52:53], v[2:3] op_sel_hi:[1,0]
	v_pk_mul_f32 v[50:51], v[50:51], v[2:3] op_sel_hi:[1,0]
	v_pk_mul_f32 v[48:49], v[48:49], v[2:3] op_sel_hi:[1,0]
	v_pk_mul_f32 v[46:47], v[46:47], v[2:3] op_sel_hi:[1,0]

; __device__ __forceinline__ void af_online_fast(f32x4 (&s)[4], bool colsel, float& m, float& l, f32x4 (&o)[8], half8 (&pf)[2], float SC) {
;     float lm = fmaxf(fmaxf(s[0][0], s[0][1]), fmaxf(s[0][2], s[0][3]));
; #pragma unroll
;     for (int kt = 1; kt < 4; ++kt) lm = fmaxf(lm, fmaxf(fmaxf(s[kt][0], s[kt][1]), fmaxf(s[kt][2], s[kt][3])));
;     if (__ballot(colsel && (lm * SC > m + 8.f)) != 0ull) {
;         float v = lm; v = fmaxf(v, __shfl_xor(v, 16)); v = fmaxf(v, __shfl_xor(v, 32));
;         const float mloc = colsel ? v * SC : -1.0e30f;
;         const float mn = fmaxf(m, mloc); const float al = __builtin_amdgcn_exp2f(m - mn); m = mn;
;         l *= al;
; #pragma unroll
;         for (int dt = 0; dt < 8; ++dt) o[dt] *= al;
;     }
.Lu2_599:
	v_max3_f32 v59, v75, v74, v77
	v_max3_f32 v66, v76, v85, v84
	v_max3_f32 v67, v82, v83, v89
	v_max3_f32 v68, v88, v86, v87
	s_nop 1
	v_max3_f32 v59, v59, v97, v96
	v_max3_f32 v66, v66, v94, v95
	v_max3_f32 v59, v59, v66, v67
	v_max_f32_e32 v59, v59, v68
	v_mul_f32_e32 v66, 0x3e0293ee, v59
	v_add_f32_e32 v67, 0x41000000, v4
	v_cmp_lt_i32_e64 s[6:7], -1, v2
	v_cmp_gt_f32_e32 vcc, v66, v67
	v_mov_b64_e32 v[72:73], v[104:105]
	v_mov_b64_e32 v[80:81], v[108:109]
	v_mov_b64_e32 v[100:101], v[112:113]
	v_mov_b64_e32 v[92:93], v[116:117]
	v_mov_b64_e32 v[68:69], v[120:121]
	v_mov_b64_e32 v[64:65], v[124:125]
	v_mov_b64_e32 v[52:53], v[128:129]
	v_mov_b64_e32 v[48:49], v[132:133]
	s_and_b64 vcc, s[6:7], vcc
	v_mov_b64_e32 v[70:71], v[102:103]
	v_mov_b64_e32 v[78:79], v[106:107]
	v_mov_b64_e32 v[98:99], v[110:111]
	v_mov_b64_e32 v[90:91], v[114:115]
	v_mov_b64_e32 v[66:67], v[118:119]
	v_mov_b64_e32 v[62:63], v[122:123]
	v_mov_b64_e32 v[50:51], v[126:127]
	v_mov_b64_e32 v[46:47], v[130:131]
	v_mov_b32_e32 v58, v5
	v_mov_b32_e32 v224, v4
	s_cbranch_vccz .Lu2_601
	ds_bpermute_b32 v66, v167, v59
	v_max_f32_e32 v67, v59, v59
	v_max_f32_e32 v68, v4, v4
	s_waitcnt lgkmcnt(0)
	v_max_f32_e32 v66, v66, v66
	v_max_f32_e32 v66, v67, v66
	ds_bpermute_b32 v67, v207, v66
	s_waitcnt lgkmcnt(0)
	v_max_f32_e32 v67, v67, v67
	v_max_f32_e32 v66, v66, v67
	v_mul_f32_e32 v66, 0x3e0293ee, v66
	v_cndmask_b32_e64 v66, v206, v66, s[6:7]
	v_max_f32_e32 v224, v68, v66
	v_sub_f32_e32 v66, v4, v224
	v_exp_f32_e32 v46, v66
	s_nop 0
	v_mul_f32_e32 v58, v5, v46
	v_pk_mul_f32 v[72:73], v[104:105], v[46:47] op_sel_hi:[1,0]
	v_pk_mul_f32 v[70:71], v[102:103], v[46:47] op_sel_hi:[1,0]
	v_pk_mul_f32 v[80:81], v[108:109], v[46:47] op_sel_hi:[1,0]
	v_pk_mul_f32 v[78:79], v[106:107], v[46:47] op_sel_hi:[1,0]
	v_pk_mul_f32 v[100:101], v[112:113], v[46:47] op_sel_hi:[1,0]
	v_pk_mul_f32 v[98:99], v[110:111], v[46:47] op_sel_hi:[1,0]
	v_pk_mul_f32 v[92:93], v[116:117], v[46:47] op_sel_hi:[1,0]
	v_pk_mul_f32 v[90:91], v[114:115], v[46:47] op_sel_hi:[1,0]
	v_pk_mul_f32 v[68:69], v[120:121], v[46:47] op_sel_hi:[1,0]
	v_pk_mul_f32 v[66:67], v[118:119], v[46:47] op_sel_hi:[1,0]
	v_pk_mul_f32 v[64:65], v[124:125], v[46:47] op_sel_hi:[1,0]
	v_pk_mul_f32 v[62:63], v[122:123], v[46:47] op_sel_hi:[1,0]
	v_pk_mul_f32 v[52:53], v[128:129], v[46:47] op_sel_hi:[1,0]
	v_pk_mul_f32 v[50:51], v[126:127], v[46:47] op_sel_hi:[1,0]
	v_pk_mul_f32 v[48:49], v[132:133], v[46:47] op_sel_hi:[1,0]
	v_pk_mul_f32 v[46:47], v[130:131], v[46:47] op_sel_hi:[1,0]

; __device__ __forceinline__ void af_online_fast(f32x4 (&s)[4], bool colsel, float& m, float& l, f32x4 (&o)[8], half8 (&pf)[2], float SC) {
;     float lm = fmaxf(fmaxf(s[0][0], s[0][1]), fmaxf(s[0][2], s[0][3]));
; #pragma unroll
;     for (int kt = 1; kt < 4; ++kt) lm = fmaxf(lm, fmaxf(fmaxf(s[kt][0], s[kt][1]), fmaxf(s[kt][2], s[kt][3])));
;     if (__ballot(colsel && (lm * SC > m + 8.f)) != 0ull) {
;         float v = lm; v = fmaxf(v, __shfl_xor(v, 16)); v = fmaxf(v, __shfl_xor(v, 32));
;         const float mloc = colsel ? v * SC : -1.0e30f;
;         const float mn = fmaxf(m, mloc); const float al = __builtin_amdgcn_exp2f(m - mn); m = mn;
;         l *= al;
; #pragma unroll
;         for (int dt = 0; dt < 8; ++dt) o[dt] *= al;
;     }
.Lu2_606:
	v_max3_f32 v59, v63, v62, v65
	v_max3_f32 v74, v64, v85, v84
	v_max3_f32 v75, v82, v83, v89
	v_max3_f32 v76, v88, v86, v87
	s_nop 1
	v_max3_f32 v59, v59, v97, v96
	v_max3_f32 v74, v74, v94, v95
	v_max3_f32 v59, v59, v74, v75
	v_max_f32_e32 v59, v59, v76
	v_mul_f32_e32 v74, 0x3e0293ee, v59
	v_add_f32_e32 v75, 0x41000000, v217
	v_cmp_lt_i32_e64 s[6:7], -1, v219
	v_cmp_gt_f32_e32 vcc, v74, v75
	v_mov_b64_e32 v[76:77], v[164:165]
	v_mov_b64_e32 v[68:69], v[160:161]
	v_mov_b64_e32 v[52:53], v[156:157]
	v_mov_b64_e32 v[48:49], v[152:153]
	v_mov_b64_e32 v[72:73], v[148:149]
	v_mov_b64_e32 v[80:81], v[144:145]
	v_mov_b64_e32 v[92:93], v[140:141]
	v_mov_b64_e32 v[100:101], v[136:137]
	s_and_b64 vcc, s[6:7], vcc
	v_mov_b64_e32 v[74:75], v[162:163]
	v_mov_b64_e32 v[66:67], v[158:159]
	v_mov_b64_e32 v[50:51], v[154:155]
	v_mov_b64_e32 v[46:47], v[150:151]
	v_mov_b64_e32 v[70:71], v[146:147]
	v_mov_b64_e32 v[78:79], v[142:143]
	v_mov_b64_e32 v[90:91], v[138:139]
	v_mov_b64_e32 v[98:99], v[134:135]
	v_mov_b32_e32 v58, v216
	v_mov_b32_e32 v221, v217
	s_cbranch_vccz .Lu2_608
	ds_bpermute_b32 v74, v167, v59
	v_max_f32_e32 v75, v59, v59
	v_max_f32_e32 v76, v217, v217
	s_waitcnt lgkmcnt(0)
	v_max_f32_e32 v74, v74, v74
	v_max_f32_e32 v74, v75, v74
	ds_bpermute_b32 v75, v207, v74
	s_waitcnt lgkmcnt(0)
	v_max_f32_e32 v75, v75, v75
	v_max_f32_e32 v74, v74, v75
	v_mul_f32_e32 v74, 0x3e0293ee, v74
	v_cndmask_b32_e64 v74, v206, v74, s[6:7]
	v_max_f32_e32 v221, v76, v74
	v_sub_f32_e32 v74, v217, v221
	v_exp_f32_e32 v74, v74
	s_nop 0
	v_mul_f32_e32 v58, v216, v74
	v_pk_mul_f32 v[100:101], v[136:137], v[74:75] op_sel_hi:[1,0]
	v_pk_mul_f32 v[98:99], v[134:135], v[74:75] op_sel_hi:[1,0]
	v_pk_mul_f32 v[92:93], v[140:141], v[74:75] op_sel_hi:[1,0]
	v_pk_mul_f32 v[90:91], v[138:139], v[74:75] op_sel_hi:[1,0]
	v_pk_mul_f32 v[80:81], v[144:145], v[74:75] op_sel_hi:[1,0]
	v_pk_mul_f32 v[78:79], v[142:143], v[74:75] op_sel_hi:[1,0]
	v_pk_mul_f32 v[72:73], v[148:149], v[74:75] op_sel_hi:[1,0]
	v_pk_mul_f32 v[70:71], v[146:147], v[74:75] op_sel_hi:[1,0]
	v_pk_mul_f32 v[48:49], v[152:153], v[74:75] op_sel_hi:[1,0]
	v_pk_mul_f32 v[46:47], v[150:151], v[74:75] op_sel_hi:[1,0]
	v_pk_mul_f32 v[52:53], v[156:157], v[74:75] op_sel_hi:[1,0]
	v_pk_mul_f32 v[50:51], v[154:155], v[74:75] op_sel_hi:[1,0]
	v_pk_mul_f32 v[68:69], v[160:161], v[74:75] op_sel_hi:[1,0]
	v_pk_mul_f32 v[66:67], v[158:159], v[74:75] op_sel_hi:[1,0]
	v_pk_mul_f32 v[76:77], v[164:165], v[74:75] op_sel_hi:[1,0]
	v_pk_mul_f32 v[74:75], v[162:163], v[74:75] op_sel_hi:[1,0]

; #define LAS __attribute__((address_space(3)))
; template <bool a0, bool a1> __device__ __forceinline__ void af_qk(const LAS unsigned char* kbuf, const unsigned (&kl)[4], const half8 (&qf)[2][4], f32x4 (&s)[2][4]) {
;     const LAS unsigned char* ka[4];
;     { int _ln; asm volatile("v_mov_b32 %0, %1" : "=v"(_ln) : "v"(kl[0]));
;       const int fr_ = _ln & 15, e_ = (_ln >> 4) ^ fr_;
; #pragma unroll
;       for (int ks = 0; ks < 4; ++ks) ka[ks] = kbuf + fr_ * 256 + ((e_ ^ (4 * ks)) << 4); }
;     half8 kf[2][4];
; #pragma unroll
;     for (int ks = 0; ks < 4; ++ks) kf[0][ks] = *(const LAS half8*)(ka[ks]);
; #pragma unroll
;     for (int kt = 0; kt < 4; ++kt) {
;         if (kt < 3) {
; #pragma unroll
;             for (int ks = 0; ks < 4; ++ks) kf[(kt + 1) & 1][ks] = *(const LAS half8*)(ka[ks] + (kt + 1) * 4096); }
;         s[0][kt] = (f32x4){0.f, 0.f, 0.f, 0.f}; s[1][kt] = (f32x4){0.f, 0.f, 0.f, 0.f};
; #pragma unroll
;         for (int ks = 0; ks < 4; ++ks) {
;             if (a0) s[0][kt] = __builtin_amdgcn_mfma_f32_16x16x32_f16(kf[kt & 1][ks], qf[0][ks], s[0][kt], 0, 0, 0);
;             if (a1) s[1][kt] = __builtin_amdgcn_mfma_f32_16x16x32_f16(kf[kt & 1][ks], qf[1][ks], s[1][kt], 0, 0, 0); }
;         __builtin_amdgcn_sched_barrier(0);
;     }
; }
; __device__ __forceinline__ void af_maskraw(f32x4 (&s)[4], int mbase, int mstep, int fq, int hi, int lo) {
; #pragma unroll
;     for (int kt = 0; kt < 4; ++kt)
; #pragma unroll
;         for (int jj = 0; jj < 4; ++jj) { const int met = mbase + mstep * (16 * kt + 4 * fq + jj); s[kt][jj] = (met <= hi && met > lo) ? s[kt][jj] : -3.0e38f; }
; }
.Lu2_610:
	s_andn2_b64 vcc, exec, s[6:7]
	s_cbranch_vccnz .Lu2_619
	v_mov_b32 v94, v172
	s_nop 0
	v_and_b32_e32 v95, 15, v94
	v_lshl_add_u32 v50, v95, 8, s64
	v_lshlrev_b32_e32 v95, 4, v95
	v_bitop3_b32 v51, v95, v94, -16 bitop3:0x78
	v_add_u32_e32 v94, v50, v51
	v_xad_u32 v95, v51, 64, v50
	v_xad_u32 v96, v51, s77, v50
	v_xad_u32 v97, v51, s78, v50
	ds_read_b128 v[98:101], v94
	ds_read_b128 v[90:93], v95
	ds_read_b128 v[78:81], v96
	ds_read_b128 v[70:73], v97
	ds_read_b128 v[58:61], v94 offset:4096
	ds_read_b128 v[54:57], v95 offset:4096
	ds_read_b128 v[42:45], v96 offset:4096
	ds_read_b128 v[38:41], v97 offset:4096
	s_waitcnt lgkmcnt(4)
	v_mfma_f32_16x16x32_f16 v[46:49], v[98:101], v[6:9], 0
	v_mfma_f32_16x16x32_f16 v[74:77], v[98:101], v[22:25], 0
	v_mfma_f32_16x16x32_f16 v[46:49], v[90:93], v[10:13], v[46:49]
	v_mfma_f32_16x16x32_f16 v[74:77], v[90:93], v[26:29], v[74:77]
	v_mfma_f32_16x16x32_f16 v[46:49], v[78:81], v[14:17], v[46:49]
	v_mfma_f32_16x16x32_f16 v[74:77], v[78:81], v[30:33], v[74:77]
	v_mfma_f32_16x16x32_f16 v[46:49], v[70:73], v[18:21], v[46:49]
	v_mfma_f32_16x16x32_f16 v[74:77], v[70:73], v[34:37], v[74:77]
	ds_read_b128 v[98:101], v94 offset:8192
	ds_read_b128 v[90:93], v95 offset:8192
	ds_read_b128 v[78:81], v96 offset:8192
	ds_read_b128 v[70:73], v97 offset:8192
	s_waitcnt lgkmcnt(4)
	v_mfma_f32_16x16x32_f16 v[50:53], v[58:61], v[6:9], 0
	v_mfma_f32_16x16x32_f16 v[82:85], v[58:61], v[22:25], 0
	v_mfma_f32_16x16x32_f16 v[50:53], v[54:57], v[10:13], v[50:53]
	v_mfma_f32_16x16x32_f16 v[82:85], v[54:57], v[26:29], v[82:85]
	v_mfma_f32_16x16x32_f16 v[50:53], v[42:45], v[14:17], v[50:53]
	v_mfma_f32_16x16x32_f16 v[82:85], v[42:45], v[30:33], v[82:85]
	v_mfma_f32_16x16x32_f16 v[50:53], v[38:41], v[18:21], v[50:53]
	v_mfma_f32_16x16x32_f16 v[82:85], v[38:41], v[34:37], v[82:85]
	ds_read_b128 v[58:61], v94 offset:12288
	ds_read_b128 v[54:57], v95 offset:12288
	ds_read_b128 v[42:45], v96 offset:12288
	ds_read_b128 v[38:41], v97 offset:12288
	s_waitcnt lgkmcnt(4)
	v_mfma_f32_16x16x32_f16 v[62:65], v[98:101], v[6:9], 0
	v_mfma_f32_16x16x32_f16 v[86:89], v[98:101], v[22:25], 0
	v_mfma_f32_16x16x32_f16 v[62:65], v[90:93], v[10:13], v[62:65]
	v_mfma_f32_16x16x32_f16 v[86:89], v[90:93], v[26:29], v[86:89]
	v_mfma_f32_16x16x32_f16 v[62:65], v[78:81], v[14:17], v[62:65]
	v_mfma_f32_16x16x32_f16 v[86:89], v[78:81], v[30:33], v[86:89]
	v_mfma_f32_16x16x32_f16 v[62:65], v[70:73], v[18:21], v[62:65]
	v_mfma_f32_16x16x32_f16 v[86:89], v[70:73], v[34:37], v[86:89]
	s_waitcnt lgkmcnt(0)
	v_mfma_f32_16x16x32_f16 v[66:69], v[58:61], v[6:9], 0
	v_mfma_f32_16x16x32_f16 v[94:97], v[58:61], v[22:25], 0
	v_mfma_f32_16x16x32_f16 v[66:69], v[54:57], v[10:13], v[66:69]
	v_mfma_f32_16x16x32_f16 v[94:97], v[54:57], v[26:29], v[94:97]
	v_mfma_f32_16x16x32_f16 v[66:69], v[42:45], v[14:17], v[66:69]
	v_mfma_f32_16x16x32_f16 v[94:97], v[42:45], v[30:33], v[94:97]
	v_mfma_f32_16x16x32_f16 v[66:69], v[38:41], v[18:21], v[66:69]
	v_mfma_f32_16x16x32_f16 v[94:97], v[38:41], v[34:37], v[94:97]
	s_nop 5
	v_cndmask_b32_e64 v98, 0, 1, s[60:61]
	v_cmp_ne_u32_e64 s[8:9], 1, v98
	s_andn2_b64 vcc, exec, s[60:61]
	s_cbranch_vccnz .Lu2_613
	v_add_u32_e32 v72, s16, v173
	v_add_u32_e32 v71, 2, v72
	v_add_u32_e32 v70, 3, v72
	v_add_u32_e32 v81, 16, v72
	v_add_u32_e32 v80, 17, v72
	v_add_u32_e32 v79, 18, v72
	v_add_u32_e32 v78, 19, v72
	v_add_u32_e32 v93, 32, v72
	v_add_u32_e32 v92, 33, v72
	v_add_u32_e32 v91, 34, v72
	v_add_u32_e32 v90, 35, v72
	v_add_u32_e32 v101, 48, v72
	v_add_u32_e32 v100, 49, v72
	v_add_u32_e32 v99, 50, v72
	v_add_u32_e32 v98, 51, v72
	v_cmp_le_i32_e32 vcc, v72, v219
	v_cmp_gt_i32_e64 s[6:7], v72, v220
	s_and_b64 vcc, vcc, s[6:7]
	v_cndmask_b32_e32 v46, v202, v46, vcc
	v_cmp_lt_i32_e32 vcc, v72, v219
	v_cmp_ge_i32_e64 s[6:7], v72, v220
	s_and_b64 vcc, vcc, s[6:7]
	v_cndmask_b32_e32 v47, v202, v47, vcc
	v_cmp_le_i32_e32 vcc, v71, v219
	v_cmp_gt_i32_e64 s[6:7], v71, v220
	s_and_b64 vcc, vcc, s[6:7]
	v_cndmask_b32_e32 v48, v202, v48, vcc
	v_cmp_le_i32_e32 vcc, v70, v219
	v_cmp_gt_i32_e64 s[6:7], v70, v220
	s_and_b64 vcc, vcc, s[6:7]
	v_cndmask_b32_e32 v49, v202, v49, vcc
	v_cmp_le_i32_e32 vcc, v81, v219
	v_cmp_gt_i32_e64 s[6:7], v81, v220
	s_and_b64 vcc, vcc, s[6:7]
	v_cndmask_b32_e32 v50, v202, v50, vcc
	v_cmp_le_i32_e32 vcc, v80, v219
	v_cmp_gt_i32_e64 s[6:7], v80, v220
	s_and_b64 vcc, vcc, s[6:7]
	v_cndmask_b32_e32 v51, v202, v51, vcc
	v_cmp_le_i32_e32 vcc, v79, v219
	v_cmp_gt_i32_e64 s[6:7], v79, v220
	s_and_b64 vcc, vcc, s[6:7]
	v_cndmask_b32_e32 v52, v202, v52, vcc
	v_cmp_le_i32_e32 vcc, v78, v219
	v_cmp_gt_i32_e64 s[6:7], v78, v220
	s_and_b64 vcc, vcc, s[6:7]
	v_cndmask_b32_e32 v53, v202, v53, vcc
	v_cmp_le_i32_e32 vcc, v93, v219
	v_cmp_gt_i32_e64 s[6:7], v93, v220
	s_and_b64 vcc, vcc, s[6:7]
	v_cndmask_b32_e32 v62, v202, v62, vcc
	v_cmp_le_i32_e32 vcc, v92, v219
	v_cmp_gt_i32_e64 s[6:7], v92, v220
	s_and_b64 vcc, vcc, s[6:7]
	v_cndmask_b32_e32 v63, v202, v63, vcc
	v_cmp_le_i32_e32 vcc, v91, v219
	v_cmp_gt_i32_e64 s[6:7], v91, v220
	s_and_b64 vcc, vcc, s[6:7]
	v_cndmask_b32_e32 v64, v202, v64, vcc
	v_cmp_le_i32_e32 vcc, v90, v219
	v_cmp_gt_i32_e64 s[6:7], v90, v220
	s_and_b64 vcc, vcc, s[6:7]
	v_cndmask_b32_e32 v65, v202, v65, vcc
	v_cmp_le_i32_e32 vcc, v101, v219
	v_cmp_gt_i32_e64 s[6:7], v101, v220
	s_and_b64 vcc, vcc, s[6:7]
	v_cndmask_b32_e32 v66, v202, v66, vcc
	v_cmp_le_i32_e32 vcc, v100, v219
	v_cmp_gt_i32_e64 s[6:7], v100, v220
	s_and_b64 vcc, vcc, s[6:7]
	v_cndmask_b32_e32 v67, v202, v67, vcc
	v_cmp_le_i32_e32 vcc, v99, v219
	v_cmp_gt_i32_e64 s[6:7], v99, v220
	s_and_b64 vcc, vcc, s[6:7]
	v_cndmask_b32_e32 v68, v202, v68, vcc
	v_cmp_le_i32_e32 vcc, v98, v219
	v_cmp_gt_i32_e64 s[6:7], v98, v220
	s_and_b64 vcc, vcc, s[6:7]
	v_cndmask_b32_e32 v69, v202, v69, vcc
; __device__ __forceinline__ void af_online_fast(f32x4 (&s)[4], bool colsel, float& m, float& l, f32x4 (&o)[8], half8 (&pf)[2], float SC) {
;     float lm = fmaxf(fmaxf(s[0][0], s[0][1]), fmaxf(s[0][2], s[0][3]));
; #pragma unroll
;     for (int kt = 1; kt < 4; ++kt) lm = fmaxf(lm, fmaxf(fmaxf(s[kt][0], s[kt][1]), fmaxf(s[kt][2], s[kt][3])));
;     if (__ballot(colsel && (lm * SC > m + 8.f)) != 0ull) {
;         float v = lm; v = fmaxf(v, __shfl_xor(v, 16)); v = fmaxf(v, __shfl_xor(v, 32));
;         const float mloc = colsel ? v * SC : -1.0e30f;
;         const float mn = fmaxf(m, mloc); const float al = __builtin_amdgcn_exp2f(m - mn); m = mn;
;         l *= al;
; #pragma unroll
;         for (int dt = 0; dt < 8; ++dt) o[dt] *= al;
;     }
.Lu2_613:
	v_max3_f32 v73, v47, v46, v49
	v_max3_f32 v58, v48, v53, v52
	v_max3_f32 v59, v50, v51, v65
	v_max3_f32 v60, v64, v69, v68
	v_max3_f32 v73, v73, v62, v63
	v_max3_f32 v58, v58, v66, v67
	v_max3_f32 v73, v73, v58, v59
	v_max_f32_e32 v73, v73, v60
	v_mul_f32_e32 v58, 0x3e0293ee, v73
	v_add_f32_e32 v59, 0x41000000, v217
	v_cmp_lt_i32_e64 s[6:7], -1, v219
	v_cmp_gt_f32_e32 vcc, v58, v59
	s_and_b64 vcc, s[6:7], vcc
	s_cbranch_vccz .Lu2_621
	ds_bpermute_b32 v58, v167, v73
	v_max_f32_e32 v73, v73, v73
	s_waitcnt lgkmcnt(0)
	v_max_f32_e32 v58, v58, v58
	v_max_f32_e32 v73, v73, v58
	ds_bpermute_b32 v58, v207, v73
	s_waitcnt lgkmcnt(0)
	v_max_f32_e32 v58, v58, v58
	v_max_f32_e32 v73, v73, v58
	v_mul_f32_e32 v73, 0x3e0293ee, v73
	v_cndmask_b32_e64 v73, v206, v73, s[6:7]
	v_max_f32_e32 v58, v217, v217
	v_max_f32_e32 v221, v58, v73
	v_sub_f32_e32 v73, v217, v221
	v_exp_f32_e32 v58, v73
	s_nop 0
	v_mul_f32_e32 v216, v216, v58
	v_pk_mul_f32 v[136:137], v[136:137], v[58:59] op_sel_hi:[1,0]
	v_pk_mul_f32 v[134:135], v[134:135], v[58:59] op_sel_hi:[1,0]
	v_pk_mul_f32 v[140:141], v[140:141], v[58:59] op_sel_hi:[1,0]
	v_pk_mul_f32 v[138:139], v[138:139], v[58:59] op_sel_hi:[1,0]
	v_pk_mul_f32 v[144:145], v[144:145], v[58:59] op_sel_hi:[1,0]
	v_pk_mul_f32 v[142:143], v[142:143], v[58:59] op_sel_hi:[1,0]
	v_pk_mul_f32 v[148:149], v[148:149], v[58:59] op_sel_hi:[1,0]
	v_pk_mul_f32 v[146:147], v[146:147], v[58:59] op_sel_hi:[1,0]
	v_pk_mul_f32 v[152:153], v[152:153], v[58:59] op_sel_hi:[1,0]
	v_pk_mul_f32 v[150:151], v[150:151], v[58:59] op_sel_hi:[1,0]
	v_pk_mul_f32 v[156:157], v[156:157], v[58:59] op_sel_hi:[1,0]
	v_pk_mul_f32 v[154:155], v[154:155], v[58:59] op_sel_hi:[1,0]
	v_pk_mul_f32 v[160:161], v[160:161], v[58:59] op_sel_hi:[1,0]
	v_pk_mul_f32 v[158:159], v[158:159], v[58:59] op_sel_hi:[1,0]
	v_pk_mul_f32 v[164:165], v[164:165], v[58:59] op_sel_hi:[1,0]
	v_pk_mul_f32 v[162:163], v[162:163], v[58:59] op_sel_hi:[1,0]
	s_and_b64 vcc, exec, s[8:9]
	s_cbranch_vccnz .Lu2_616

; __device__ __forceinline__ void af_online_fast(f32x4 (&s)[4], bool colsel, float& m, float& l, f32x4 (&o)[8], half8 (&pf)[2], float SC) {
;     float lm = fmaxf(fmaxf(s[0][0], s[0][1]), fmaxf(s[0][2], s[0][3]));
; #pragma unroll
;     for (int kt = 1; kt < 4; ++kt) lm = fmaxf(lm, fmaxf(fmaxf(s[kt][0], s[kt][1]), fmaxf(s[kt][2], s[kt][3])));
;     if (__ballot(colsel && (lm * SC > m + 8.f)) != 0ull) {
;         float v = lm; v = fmaxf(v, __shfl_xor(v, 16)); v = fmaxf(v, __shfl_xor(v, 32));
;         const float mloc = colsel ? v * SC : -1.0e30f;
;         const float mn = fmaxf(m, mloc); const float al = __builtin_amdgcn_exp2f(m - mn); m = mn;
;         l *= al;
; #pragma unroll
;         for (int dt = 0; dt < 8; ++dt) o[dt] *= al;
;     }
.Lu2_616:
	v_cmp_lt_i32_e64 s[8:9], -1, v2
	v_max3_f32 v2, v75, v74, v77
	v_max3_f32 v98, v76, v85, v84
	v_max3_f32 v99, v82, v83, v89
	v_max3_f32 v100, v88, v97, v96
	v_max3_f32 v2, v2, v86, v87
	v_max3_f32 v98, v98, v94, v95
	v_max3_f32 v2, v2, v98, v99
	v_max_f32_e32 v2, v2, v100
	v_mul_f32_e32 v98, 0x3e0293ee, v2
	v_add_f32_e32 v99, 0x41000000, v4
	v_cmp_gt_f32_e32 vcc, v98, v99
	s_and_b64 vcc, s[8:9], vcc
	s_cbranch_vccz .Lu2_618
	ds_bpermute_b32 v98, v167, v2
	v_max_f32_e32 v2, v2, v2
	s_waitcnt lgkmcnt(0)
	v_max_f32_e32 v98, v98, v98
	v_max_f32_e32 v2, v2, v98
	ds_bpermute_b32 v98, v207, v2
	s_waitcnt lgkmcnt(0)
	v_max_f32_e32 v98, v98, v98
	v_max_f32_e32 v2, v2, v98
	v_mul_f32_e32 v2, 0x3e0293ee, v2
	v_cndmask_b32_e64 v2, v206, v2, s[8:9]
	v_max_f32_e32 v98, v4, v4
	v_max_f32_e32 v98, v98, v2
	v_sub_f32_e32 v2, v4, v98
	v_exp_f32_e32 v2, v2
	v_mov_b32_e32 v4, v98
	v_mul_f32_e32 v5, v5, v2
	v_pk_mul_f32 v[104:105], v[104:105], v[2:3] op_sel_hi:[1,0]
	v_pk_mul_f32 v[102:103], v[102:103], v[2:3] op_sel_hi:[1,0]
	v_pk_mul_f32 v[108:109], v[108:109], v[2:3] op_sel_hi:[1,0]
	v_pk_mul_f32 v[106:107], v[106:107], v[2:3] op_sel_hi:[1,0]
	v_pk_mul_f32 v[112:113], v[112:113], v[2:3] op_sel_hi:[1,0]
	v_pk_mul_f32 v[110:111], v[110:111], v[2:3] op_sel_hi:[1,0]
	v_pk_mul_f32 v[116:117], v[116:117], v[2:3] op_sel_hi:[1,0]
	v_pk_mul_f32 v[114:115], v[114:115], v[2:3] op_sel_hi:[1,0]
	v_pk_mul_f32 v[120:121], v[120:121], v[2:3] op_sel_hi:[1,0]
	v_pk_mul_f32 v[118:119], v[118:119], v[2:3] op_sel_hi:[1,0]
	v_pk_mul_f32 v[124:125], v[124:125], v[2:3] op_sel_hi:[1,0]
	v_pk_mul_f32 v[122:123], v[122:123], v[2:3] op_sel_hi:[1,0]
	v_pk_mul_f32 v[128:129], v[128:129], v[2:3] op_sel_hi:[1,0]
	v_pk_mul_f32 v[126:127], v[126:127], v[2:3] op_sel_hi:[1,0]
	v_pk_mul_f32 v[132:133], v[132:133], v[2:3] op_sel_hi:[1,0]
	v_pk_mul_f32 v[130:131], v[130:131], v[2:3] op_sel_hi:[1,0]
